# one s_nop per K-loop iteration after 3rd MMA cluster: re-aligns 4th MFMA cluster and LB load cluster to 8 bytes
# baseline (speedup 1.0000x reference)
; #define PG8_STAGE(bufoff, gbase, voff) do { _Pragma("unroll") for (int _i = 0; _i < 2; ++_i) \
;         __builtin_amdgcn_global_load_lds((const unsigned*)((const char*)(gbase) + (voff)[_i]), (LAS unsigned*)(lds + (bufoff) + ldsw + _i * 8192), 16, 0, 0); } while (0)
; #define PG8_LDA(dst, b, h) do { _Pragma("unroll") for (int m = 0; m < 4; ++m) _Pragma("unroll") for (int k = 0; k < 2; ++k) dst[m][k] = *(const LAS bf16x8*)(lds + PG8_SA(b, h) + aoff + m * 2048 + k * 1024); } while (0)
; #define PG8_LDB(dst, b, h) do { _Pragma("unroll") for (int n = 0; n < 2; ++n) _Pragma("unroll") for (int k = 0; k < 2; ++k) dst[n][k] = *(const LAS bf16x8*)(lds + PG8_SB(b, h) + boff + n * 2048 + k * 1024); } while (0)
; #define PG8_MMA(ai, bj, At, Bt) do { __builtin_amdgcn_s_setprio(1); _Pragma("unroll") for (int m = 0; m < 4; ++m) _Pragma("unroll") for (int n = 0; n < 2; ++n) _Pragma("unroll") for (int k = 0; k < 2; ++k) \
;         acc[ai][bj][m][n] = __builtin_amdgcn_mfma_f32_16x16x32_bf16(Bt[n][k], At[m][k], acc[ai][bj][m][n], 0, 0, 0); __builtin_amdgcn_s_setprio(0); } while (0)
; #define PG8_WAIT_V(n) asm volatile("s_waitcnt vmcnt(" #n ")" ::: "memory")
; #define PG8_WAIT_L(n) asm volatile("s_waitcnt lgkmcnt(" #n ")" ::: "memory")
; #define PG8_BAR __builtin_amdgcn_s_barrier()
; #define PG8_SCHED __builtin_amdgcn_sched_barrier(0)
; template <class Prog>
; __device__ __forceinline__ void gemm_phase(LAS unsigned char* lds, const int K, const Prog& S) {
;     ...
;             PG8_LDB(B0, 0, 0); PG8_SCHED; PG8_LDA(At, 0, 0); PG8_STAGE(PG8_SA(1, 1), a1 + hstep, voffA);
;             PG8_WAIT_L(8); PG8_BAR; PG8_WAIT_L(0); PG8_MMA(0, 0, At, B0); PG8_BAR; PG8_SCHED;
;             PG8_LDB(B1, 0, 1); PG8_STAGE(PG8_SB(0, 0), b2, voffB);
;             PG8_BAR; PG8_WAIT_L(0); PG8_MMA(0, 1, At, B1); PG8_BAR;
;             PG8_LDA(At, 0, 1); PG8_STAGE(PG8_SA(0, 0), a2, voffA);
;             PG8_BAR; PG8_WAIT_L(0); PG8_MMA(1, 0, At, B0); PG8_BAR; PG8_SCHED;
;             PG8_STAGE(PG8_SB(0, 1), b2 + hstep, voffB);
;             PG8_WAIT_V(6); PG8_BAR; PG8_MMA(1, 1, At, B1); PG8_BAR;
.LBB0_100:
	s_add_u32 s40, s40, 0x80080
	s_addc_u32 s41, s41, 0
	s_add_u32 s9, s44, 0x100
	s_addc_u32 s15, s45, 0
	s_mov_b32 s69, -2
	s_waitcnt vmcnt(16)
	v_add_u32_e32 v244, 0x10000, v205
	s_add_u32 s44, s40, 0xfff80080
	s_addc_u32 s45, s41, -1
	s_cmp_eq_u32 s69, 28
	s_cselect_b32 s47, s5, s45
	s_cselect_b32 s46, s4, s44
	s_cselect_b32 s45, s13, s15
	s_cselect_b32 s44, s12, s9
	s_add_u32 s76, s40, 0xfff80000
	s_addc_u32 s77, s41, -1
	ds_read_b128 v[128:131], v244
	ds_read_b128 v[132:135], v244 offset:1024
	ds_read_b128 v[136:139], v244 offset:2048
	ds_read_b128 v[140:143], v244 offset:3072
	s_add_i32 m0, s92, 0x8000
	ds_read_b128 v[188:191], v244 offset:16384
	ds_read_b128 v[196:199], v244 offset:17408
	ds_read_b128 v[200:203], v244 offset:18432
	ds_read_b128 v[218:221], v244 offset:19456
	global_load_lds_dwordx4 v184, s[76:77]
	s_add_i32 m0, s92, 0xa000
	ds_read_b128 v[144:147], v216
	ds_read_b128 v[148:151], v216 offset:1024
	ds_read_b128 v[152:155], v216 offset:2048
	ds_read_b128 v[156:159], v216 offset:3072
	global_load_lds_dwordx4 v186, s[76:77]
	s_add_i32 m0, s92, 0xc000
	ds_read_b128 v[160:163], v216 offset:4096
	ds_read_b128 v[164:167], v216 offset:5120
	ds_read_b128 v[168:171], v216 offset:6144
	ds_read_b128 v[172:175], v216 offset:7168
	global_load_lds_dwordx4 v184, s[40:41]
	s_add_i32 m0, s92, 0xe000
	s_nop 0
	global_load_lds_dwordx4 v186, s[40:41]
	s_waitcnt lgkmcnt(0)
	s_barrier
	v_mfma_f32_16x16x32_bf16 v[124:127], v[128:131], v[144:147], 0
	v_mfma_f32_16x16x32_bf16 v[116:119], v[136:139], v[144:147], 0
	v_mfma_f32_16x16x32_bf16 v[108:111], v[128:131], v[152:155], 0
	v_mfma_f32_16x16x32_bf16 v[100:103], v[136:139], v[152:155], 0
	v_mfma_f32_16x16x32_bf16 v[92:95], v[128:131], v[160:163], 0
	v_mfma_f32_16x16x32_bf16 v[84:87], v[136:139], v[160:163], 0
	v_mfma_f32_16x16x32_bf16 v[76:79], v[128:131], v[168:171], 0
	v_mfma_f32_16x16x32_bf16 v[68:71], v[136:139], v[168:171], 0
	v_mfma_f32_16x16x32_bf16 v[124:127], v[132:135], v[148:151], v[124:127]
	v_mfma_f32_16x16x32_bf16 v[116:119], v[140:143], v[148:151], v[116:119]
	v_mfma_f32_16x16x32_bf16 v[108:111], v[132:135], v[156:159], v[108:111]
	v_mfma_f32_16x16x32_bf16 v[100:103], v[140:143], v[156:159], v[100:103]
	v_mfma_f32_16x16x32_bf16 v[92:95], v[132:135], v[164:167], v[92:95]
	v_mfma_f32_16x16x32_bf16 v[84:87], v[140:143], v[164:167], v[84:87]
	v_mfma_f32_16x16x32_bf16 v[76:79], v[132:135], v[172:175], v[76:79]
	v_mfma_f32_16x16x32_bf16 v[68:71], v[140:143], v[172:175], v[68:71]
	v_mfma_f32_16x16x32_bf16 v[120:123], v[188:191], v[144:147], 0
	v_mfma_f32_16x16x32_bf16 v[112:115], v[200:203], v[144:147], 0
	v_mfma_f32_16x16x32_bf16 v[104:107], v[188:191], v[152:155], 0
	v_mfma_f32_16x16x32_bf16 v[96:99], v[200:203], v[152:155], 0
	v_mfma_f32_16x16x32_bf16 v[88:91], v[188:191], v[160:163], 0
	v_mfma_f32_16x16x32_bf16 v[80:83], v[200:203], v[160:163], 0
	v_mfma_f32_16x16x32_bf16 v[72:75], v[188:191], v[168:171], 0
	v_mfma_f32_16x16x32_bf16 v[64:67], v[200:203], v[168:171], 0
	v_mfma_f32_16x16x32_bf16 v[120:123], v[196:199], v[148:151], v[120:123]
	v_mfma_f32_16x16x32_bf16 v[112:115], v[218:221], v[148:151], v[112:115]
	v_mfma_f32_16x16x32_bf16 v[104:107], v[196:199], v[156:159], v[104:107]
	v_mfma_f32_16x16x32_bf16 v[96:99], v[218:221], v[156:159], v[96:99]
	v_mfma_f32_16x16x32_bf16 v[88:91], v[196:199], v[164:167], v[88:91]
	v_mfma_f32_16x16x32_bf16 v[80:83], v[218:221], v[164:167], v[80:83]
	v_mfma_f32_16x16x32_bf16 v[72:75], v[196:199], v[172:175], v[72:75]
	v_mfma_f32_16x16x32_bf16 v[64:67], v[218:221], v[172:175], v[64:67]
	s_barrier
	ds_read_b128 v[144:147], v216 offset:16384
	ds_read_b128 v[148:151], v216 offset:17408
	ds_read_b128 v[152:155], v216 offset:18432
	ds_read_b128 v[156:159], v216 offset:19456
	s_add_i32 m0, s92, 0x10000
	ds_read_b128 v[160:163], v216 offset:20480
	ds_read_b128 v[164:167], v216 offset:21504
	ds_read_b128 v[168:171], v216 offset:22528
	ds_read_b128 v[172:175], v216 offset:23552
	global_load_lds_dwordx4 v192, s[44:45]
	s_add_i32 m0, s92, 0x12000
	s_nop 0
	global_load_lds_dwordx4 v180, s[44:45]
	s_add_u32 s76, s44, 0x80000
	s_addc_u32 s77, s45, 0
	s_add_i32 m0, s92, 0x14000
	s_nop 0
	global_load_lds_dwordx4 v192, s[76:77]
	s_add_i32 m0, s92, 0x16000
	s_nop 0
	global_load_lds_dwordx4 v180, s[76:77]
	s_waitcnt vmcnt(4)
	s_waitcnt lgkmcnt(0)
	s_barrier
	v_mfma_f32_16x16x32_bf16 v[60:63], v[128:131], v[144:147], 0
	v_mfma_f32_16x16x32_bf16 v[52:55], v[136:139], v[144:147], 0
	v_mfma_f32_16x16x32_bf16 v[44:47], v[128:131], v[152:155], 0
	v_mfma_f32_16x16x32_bf16 v[36:39], v[136:139], v[152:155], 0
	v_mfma_f32_16x16x32_bf16 v[28:31], v[128:131], v[160:163], 0
	v_mfma_f32_16x16x32_bf16 v[20:23], v[136:139], v[160:163], 0
	v_mfma_f32_16x16x32_bf16 v[12:15], v[128:131], v[168:171], 0
	v_mfma_f32_16x16x32_bf16 v[4:7], v[136:139], v[168:171], 0
	v_mfma_f32_16x16x32_bf16 v[60:63], v[132:135], v[148:151], v[60:63]
	v_mfma_f32_16x16x32_bf16 v[52:55], v[140:143], v[148:151], v[52:55]
	v_mfma_f32_16x16x32_bf16 v[44:47], v[132:135], v[156:159], v[44:47]
	v_mfma_f32_16x16x32_bf16 v[36:39], v[140:143], v[156:159], v[36:39]
	v_mfma_f32_16x16x32_bf16 v[28:31], v[132:135], v[164:167], v[28:31]
	v_mfma_f32_16x16x32_bf16 v[20:23], v[140:143], v[164:167], v[20:23]
	v_mfma_f32_16x16x32_bf16 v[12:15], v[132:135], v[172:175], v[12:15]
	v_mfma_f32_16x16x32_bf16 v[4:7], v[140:143], v[172:175], v[4:7]
	v_mfma_f32_16x16x32_bf16 v[56:59], v[188:191], v[144:147], 0
	v_mfma_f32_16x16x32_bf16 v[48:51], v[200:203], v[144:147], 0
	v_mfma_f32_16x16x32_bf16 v[40:43], v[188:191], v[152:155], 0
	v_mfma_f32_16x16x32_bf16 v[32:35], v[200:203], v[152:155], 0
	v_mfma_f32_16x16x32_bf16 v[24:27], v[188:191], v[160:163], 0
	v_mfma_f32_16x16x32_bf16 v[16:19], v[200:203], v[160:163], 0
	v_mfma_f32_16x16x32_bf16 v[8:11], v[188:191], v[168:171], 0
	v_mfma_f32_16x16x32_bf16 v[0:3], v[200:203], v[168:171], 0
	v_mfma_f32_16x16x32_bf16 v[56:59], v[196:199], v[148:151], v[56:59]
	v_mfma_f32_16x16x32_bf16 v[48:51], v[218:221], v[148:151], v[48:51]
	v_mfma_f32_16x16x32_bf16 v[40:43], v[196:199], v[156:159], v[40:43]
	v_mfma_f32_16x16x32_bf16 v[32:35], v[218:221], v[156:159], v[32:35]
	v_mfma_f32_16x16x32_bf16 v[24:27], v[196:199], v[164:167], v[24:27]
	v_mfma_f32_16x16x32_bf16 v[16:19], v[218:221], v[164:167], v[16:19]
	v_mfma_f32_16x16x32_bf16 v[8:11], v[196:199], v[172:175], v[8:11]
	v_mfma_f32_16x16x32_bf16 v[0:3], v[218:221], v[172:175], v[0:3]
	s_barrier
; #define PG8_STAGE(bufoff, gbase, voff) do { _Pragma("unroll") for (int _i = 0; _i < 2; ++_i) \
;         __builtin_amdgcn_global_load_lds((const unsigned*)((const char*)(gbase) + (voff)[_i]), (LAS unsigned*)(lds + (bufoff) + ldsw + _i * 8192), 16, 0, 0); } while (0)
; #define PG8_LDA(dst, b, h) do { _Pragma("unroll") for (int m = 0; m < 4; ++m) _Pragma("unroll") for (int k = 0; k < 2; ++k) dst[m][k] = *(const LAS bf16x8*)(lds + PG8_SA(b, h) + aoff + m * 2048 + k * 1024); } while (0)
; #define PG8_LDB(dst, b, h) do { _Pragma("unroll") for (int n = 0; n < 2; ++n) _Pragma("unroll") for (int k = 0; k < 2; ++k) dst[n][k] = *(const LAS bf16x8*)(lds + PG8_SB(b, h) + boff + n * 2048 + k * 1024); } while (0)
; #define PG8_MMA(ai, bj, At, Bt) do { __builtin_amdgcn_s_setprio(1); _Pragma("unroll") for (int m = 0; m < 4; ++m) _Pragma("unroll") for (int n = 0; n < 2; ++n) _Pragma("unroll") for (int k = 0; k < 2; ++k) \
;         acc[ai][bj][m][n] = __builtin_amdgcn_mfma_f32_16x16x32_bf16(Bt[n][k], At[m][k], acc[ai][bj][m][n], 0, 0, 0); __builtin_amdgcn_s_setprio(0); } while (0)
; #define PG8_WAIT_V(n) asm volatile("s_waitcnt vmcnt(" #n ")" ::: "memory")
; #define PG8_WAIT_L(n) asm volatile("s_waitcnt lgkmcnt(" #n ")" ::: "memory")
; #define PG8_BAR __builtin_amdgcn_s_barrier()
; #define PG8_SCHED __builtin_amdgcn_sched_barrier(0)
; template <class Prog>
; __device__ __forceinline__ void gemm_phase(LAS unsigned char* lds, const int K, const Prog& S) {
;     ...
;             PG8_LDB(B0, 1, 0); PG8_SCHED; PG8_LDA(At, 1, 0); PG8_STAGE(PG8_SA(0, 1), a2 + hstep, voffA);
;             PG8_WAIT_L(8); PG8_BAR; PG8_WAIT_L(0); PG8_MMA(0, 0, At, B0); PG8_BAR; PG8_SCHED;
;             PG8_LDB(B1, 1, 1); PG8_STAGE(PG8_SB(1, 0), b3, voffB);
;             PG8_BAR; PG8_WAIT_L(0); PG8_MMA(0, 1, At, B1); PG8_BAR;
;             PG8_LDA(At, 1, 1); PG8_STAGE(PG8_SA(1, 0), a3, voffA);
;             PG8_BAR; PG8_WAIT_L(0); PG8_MMA(1, 0, At, B0); PG8_BAR; PG8_SCHED;
;             PG8_STAGE(PG8_SB(1, 1), b3 + hstep, voffB);
;             PG8_WAIT_V(6); PG8_BAR; PG8_MMA(1, 1, At, B1); PG8_BAR;
	s_add_u32 s76, s46, 0x80000
	s_addc_u32 s77, s47, 0
	ds_read_b128 v[128:131], v244 offset:32768
	ds_read_b128 v[132:135], v244 offset:33792
	ds_read_b128 v[136:139], v244 offset:34816
	ds_read_b128 v[140:143], v244 offset:35840
	s_mov_b32 m0, s92
	ds_read_b128 v[188:191], v244 offset:49152
	ds_read_b128 v[196:199], v244 offset:50176
	ds_read_b128 v[200:203], v244 offset:51200
	ds_read_b128 v[218:221], v244 offset:52224
	global_load_lds_dwordx4 v176, s[46:47]
	s_add_i32 m0, s92, 0x2000
	ds_read_b128 v[144:147], v216 offset:32768
	ds_read_b128 v[148:151], v216 offset:33792
	ds_read_b128 v[152:155], v216 offset:34816
	ds_read_b128 v[156:159], v216 offset:35840
	global_load_lds_dwordx4 v178, s[46:47]
	s_add_i32 m0, s92, 0x4000
	ds_read_b128 v[160:163], v216 offset:36864
	ds_read_b128 v[164:167], v216 offset:37888
	ds_read_b128 v[168:171], v216 offset:38912
	ds_read_b128 v[172:175], v216 offset:39936
	global_load_lds_dwordx4 v176, s[76:77]
	s_add_i32 m0, s92, 0x6000
	s_nop 0
	global_load_lds_dwordx4 v178, s[76:77]
	s_waitcnt lgkmcnt(0)
	s_barrier
	v_mfma_f32_16x16x32_bf16 v[124:127], v[128:131], v[144:147], v[124:127]
	v_mfma_f32_16x16x32_bf16 v[116:119], v[136:139], v[144:147], v[116:119]
	v_mfma_f32_16x16x32_bf16 v[108:111], v[128:131], v[152:155], v[108:111]
	v_mfma_f32_16x16x32_bf16 v[100:103], v[136:139], v[152:155], v[100:103]
	v_mfma_f32_16x16x32_bf16 v[92:95], v[128:131], v[160:163], v[92:95]
	v_mfma_f32_16x16x32_bf16 v[84:87], v[136:139], v[160:163], v[84:87]
	v_mfma_f32_16x16x32_bf16 v[76:79], v[128:131], v[168:171], v[76:79]
	v_mfma_f32_16x16x32_bf16 v[68:71], v[136:139], v[168:171], v[68:71]
	v_mfma_f32_16x16x32_bf16 v[124:127], v[132:135], v[148:151], v[124:127]
	v_mfma_f32_16x16x32_bf16 v[116:119], v[140:143], v[148:151], v[116:119]
	v_mfma_f32_16x16x32_bf16 v[108:111], v[132:135], v[156:159], v[108:111]
	v_mfma_f32_16x16x32_bf16 v[100:103], v[140:143], v[156:159], v[100:103]
	v_mfma_f32_16x16x32_bf16 v[92:95], v[132:135], v[164:167], v[92:95]
	v_mfma_f32_16x16x32_bf16 v[84:87], v[140:143], v[164:167], v[84:87]
	v_mfma_f32_16x16x32_bf16 v[76:79], v[132:135], v[172:175], v[76:79]
	v_mfma_f32_16x16x32_bf16 v[68:71], v[140:143], v[172:175], v[68:71]
	v_mfma_f32_16x16x32_bf16 v[120:123], v[188:191], v[144:147], v[120:123]
	v_mfma_f32_16x16x32_bf16 v[112:115], v[200:203], v[144:147], v[112:115]
	v_mfma_f32_16x16x32_bf16 v[104:107], v[188:191], v[152:155], v[104:107]
	v_mfma_f32_16x16x32_bf16 v[96:99], v[200:203], v[152:155], v[96:99]
	v_mfma_f32_16x16x32_bf16 v[88:91], v[188:191], v[160:163], v[88:91]
	v_mfma_f32_16x16x32_bf16 v[80:83], v[200:203], v[160:163], v[80:83]
	v_mfma_f32_16x16x32_bf16 v[72:75], v[188:191], v[168:171], v[72:75]
	v_mfma_f32_16x16x32_bf16 v[64:67], v[200:203], v[168:171], v[64:67]
	v_mfma_f32_16x16x32_bf16 v[120:123], v[196:199], v[148:151], v[120:123]
	v_mfma_f32_16x16x32_bf16 v[112:115], v[218:221], v[148:151], v[112:115]
	v_mfma_f32_16x16x32_bf16 v[104:107], v[196:199], v[156:159], v[104:107]
	v_mfma_f32_16x16x32_bf16 v[96:99], v[218:221], v[156:159], v[96:99]
	v_mfma_f32_16x16x32_bf16 v[88:91], v[196:199], v[164:167], v[88:91]
	v_mfma_f32_16x16x32_bf16 v[80:83], v[218:221], v[164:167], v[80:83]
	v_mfma_f32_16x16x32_bf16 v[72:75], v[196:199], v[172:175], v[72:75]
	v_mfma_f32_16x16x32_bf16 v[64:67], v[218:221], v[172:175], v[64:67]
	s_nop 0
	s_barrier
	s_add_u32 s76, s44, 0x80
	s_addc_u32 s77, s45, 0
	ds_read_b128 v[144:147], v216 offset:49152
	ds_read_b128 v[148:151], v216 offset:50176
	ds_read_b128 v[152:155], v216 offset:51200
	ds_read_b128 v[156:159], v216 offset:52224
	s_add_i32 m0, s92, 0x18000
	ds_read_b128 v[160:163], v216 offset:53248
	ds_read_b128 v[164:167], v216 offset:54272
	ds_read_b128 v[168:171], v216 offset:55296
	ds_read_b128 v[172:175], v216 offset:56320
	global_load_lds_dwordx4 v192, s[76:77]
	s_add_i32 m0, s92, 0x1a000
	s_nop 0
	global_load_lds_dwordx4 v180, s[76:77]
	s_add_u32 s76, s44, 0x80080
	s_addc_u32 s77, s45, 0
	s_add_i32 m0, s92, 0x1c000
	s_nop 0
	global_load_lds_dwordx4 v192, s[76:77]
	s_add_i32 m0, s92, 0x1e000
	s_nop 0
	global_load_lds_dwordx4 v180, s[76:77]
	s_waitcnt vmcnt(4)
	s_waitcnt lgkmcnt(0)
	s_barrier
	v_mfma_f32_16x16x32_bf16 v[60:63], v[128:131], v[144:147], v[60:63]
	v_mfma_f32_16x16x32_bf16 v[52:55], v[136:139], v[144:147], v[52:55]
	v_mfma_f32_16x16x32_bf16 v[44:47], v[128:131], v[152:155], v[44:47]
	v_mfma_f32_16x16x32_bf16 v[36:39], v[136:139], v[152:155], v[36:39]
	v_mfma_f32_16x16x32_bf16 v[28:31], v[128:131], v[160:163], v[28:31]
	v_mfma_f32_16x16x32_bf16 v[20:23], v[136:139], v[160:163], v[20:23]
	v_mfma_f32_16x16x32_bf16 v[12:15], v[128:131], v[168:171], v[12:15]
	v_mfma_f32_16x16x32_bf16 v[4:7], v[136:139], v[168:171], v[4:7]
	v_mfma_f32_16x16x32_bf16 v[60:63], v[132:135], v[148:151], v[60:63]
	v_mfma_f32_16x16x32_bf16 v[52:55], v[140:143], v[148:151], v[52:55]
	v_mfma_f32_16x16x32_bf16 v[44:47], v[132:135], v[156:159], v[44:47]
	v_mfma_f32_16x16x32_bf16 v[36:39], v[140:143], v[156:159], v[36:39]
	v_mfma_f32_16x16x32_bf16 v[28:31], v[132:135], v[164:167], v[28:31]
	v_mfma_f32_16x16x32_bf16 v[20:23], v[140:143], v[164:167], v[20:23]
	v_mfma_f32_16x16x32_bf16 v[12:15], v[132:135], v[172:175], v[12:15]
	v_mfma_f32_16x16x32_bf16 v[4:7], v[140:143], v[172:175], v[4:7]
	v_mfma_f32_16x16x32_bf16 v[56:59], v[188:191], v[144:147], v[56:59]
	v_mfma_f32_16x16x32_bf16 v[48:51], v[200:203], v[144:147], v[48:51]
	v_mfma_f32_16x16x32_bf16 v[40:43], v[188:191], v[152:155], v[40:43]
	v_mfma_f32_16x16x32_bf16 v[32:35], v[200:203], v[152:155], v[32:35]
	v_mfma_f32_16x16x32_bf16 v[24:27], v[188:191], v[160:163], v[24:27]
	v_mfma_f32_16x16x32_bf16 v[16:19], v[200:203], v[160:163], v[16:19]
	v_mfma_f32_16x16x32_bf16 v[8:11], v[188:191], v[168:171], v[8:11]
	v_mfma_f32_16x16x32_bf16 v[0:3], v[200:203], v[168:171], v[0:3]
	v_mfma_f32_16x16x32_bf16 v[56:59], v[196:199], v[148:151], v[56:59]
	v_mfma_f32_16x16x32_bf16 v[48:51], v[218:221], v[148:151], v[48:51]
	v_mfma_f32_16x16x32_bf16 v[40:43], v[196:199], v[156:159], v[40:43]
	v_mfma_f32_16x16x32_bf16 v[32:35], v[218:221], v[156:159], v[32:35]
	v_mfma_f32_16x16x32_bf16 v[24:27], v[196:199], v[164:167], v[24:27]
	v_mfma_f32_16x16x32_bf16 v[16:19], v[218:221], v[164:167], v[16:19]
	v_mfma_f32_16x16x32_bf16 v[8:11], v[196:199], v[172:175], v[8:11]
	v_mfma_f32_16x16x32_bf16 v[0:3], v[218:221], v[172:175], v[0:3]
	s_add_i32 s69, s69, 2
	s_add_u32 s40, s40, 0x100
	s_addc_u32 s41, s41, 0
	s_add_u32 s9, s9, 0x100
	s_addc_u32 s15, s15, 0
	s_cmp_gt_u32 s69, 29
	s_barrier
	.p2align 6
; #define PG8_STAGE(bufoff, gbase, voff) do { _Pragma("unroll") for (int _i = 0; _i < 2; ++_i) \
;         __builtin_amdgcn_global_load_lds((const unsigned*)((const char*)(gbase) + (voff)[_i]), (LAS unsigned*)(lds + (bufoff) + ldsw + _i * 8192), 16, 0, 0); } while (0)
; #define PG8_LDA(dst, b, h) do { _Pragma("unroll") for (int m = 0; m < 4; ++m) _Pragma("unroll") for (int k = 0; k < 2; ++k) dst[m][k] = *(const LAS bf16x8*)(lds + PG8_SA(b, h) + aoff + m * 2048 + k * 1024); } while (0)
; #define PG8_LDB(dst, b, h) do { _Pragma("unroll") for (int n = 0; n < 2; ++n) _Pragma("unroll") for (int k = 0; k < 2; ++k) dst[n][k] = *(const LAS bf16x8*)(lds + PG8_SB(b, h) + boff + n * 2048 + k * 1024); } while (0)
; #define PG8_MMA(ai, bj, At, Bt) do { __builtin_amdgcn_s_setprio(1); _Pragma("unroll") for (int m = 0; m < 4; ++m) _Pragma("unroll") for (int n = 0; n < 2; ++n) _Pragma("unroll") for (int k = 0; k < 2; ++k) \
;         acc[ai][bj][m][n] = __builtin_amdgcn_mfma_f32_16x16x32_bf16(Bt[n][k], At[m][k], acc[ai][bj][m][n], 0, 0, 0); __builtin_amdgcn_s_setprio(0); } while (0)
; #define PG8_WAIT_V(n) asm volatile("s_waitcnt vmcnt(" #n ")" ::: "memory")
; #define PG8_WAIT_L(n) asm volatile("s_waitcnt lgkmcnt(" #n ")" ::: "memory")
; #define PG8_BAR __builtin_amdgcn_s_barrier()
; #define PG8_SCHED __builtin_amdgcn_sched_barrier(0)
; template <class Prog>
; __device__ __forceinline__ void gemm_phase(LAS unsigned char* lds, const int K, const Prog& S) {
;     ...
;             PG8_LDB(B0, 0, 0); PG8_SCHED; PG8_LDA(At, 0, 0); PG8_STAGE(PG8_SA(1, 1), a1 + hstep, voffA);
;             PG8_WAIT_L(8); PG8_BAR; PG8_WAIT_L(0); PG8_MMA(0, 0, At, B0); PG8_BAR; PG8_SCHED;
;             PG8_LDB(B1, 0, 1); PG8_STAGE(PG8_SB(0, 0), b2, voffB);
;             PG8_BAR; PG8_WAIT_L(0); PG8_MMA(0, 1, At, B1); PG8_BAR;
;             PG8_LDA(At, 0, 1); PG8_STAGE(PG8_SA(0, 0), a2, voffA);
;             PG8_BAR; PG8_WAIT_L(0); PG8_MMA(1, 0, At, B0); PG8_BAR; PG8_SCHED;
;             PG8_STAGE(PG8_SB(0, 1), b2 + hstep, voffB);
;             PG8_WAIT_V(6); PG8_BAR; PG8_MMA(1, 1, At, B1); PG8_BAR;
.LBB0_101:
	s_add_u32 s44, s40, 0xfff80080
	s_addc_u32 s45, s41, -1
	s_cmp_eq_u32 s69, 28
	s_cselect_b32 s47, s5, s45
	s_cselect_b32 s46, s4, s44
	s_cselect_b32 s45, s13, s15
	s_cselect_b32 s44, s12, s9
	s_add_u32 s76, s40, 0xfff80000
	s_addc_u32 s77, s41, -1
	ds_read_b128 v[128:131], v244
	ds_read_b128 v[132:135], v244 offset:1024
	ds_read_b128 v[136:139], v244 offset:2048
	ds_read_b128 v[140:143], v244 offset:3072
	s_add_i32 m0, s92, 0x8000
	ds_read_b128 v[188:191], v244 offset:16384
	ds_read_b128 v[196:199], v244 offset:17408
	ds_read_b128 v[200:203], v244 offset:18432
	ds_read_b128 v[218:221], v244 offset:19456
	global_load_lds_dwordx4 v184, s[76:77]
	s_add_i32 m0, s92, 0xa000
	ds_read_b128 v[144:147], v216
	ds_read_b128 v[148:151], v216 offset:1024
	ds_read_b128 v[152:155], v216 offset:2048
	ds_read_b128 v[156:159], v216 offset:3072
	global_load_lds_dwordx4 v186, s[76:77]
	s_add_i32 m0, s92, 0xc000
	ds_read_b128 v[160:163], v216 offset:4096
	ds_read_b128 v[164:167], v216 offset:5120
	ds_read_b128 v[168:171], v216 offset:6144
	ds_read_b128 v[172:175], v216 offset:7168
	global_load_lds_dwordx4 v184, s[40:41]
	s_add_i32 m0, s92, 0xe000
	s_nop 0
	global_load_lds_dwordx4 v186, s[40:41]
	s_waitcnt lgkmcnt(0)
	s_barrier
	v_mfma_f32_16x16x32_bf16 v[124:127], v[128:131], v[144:147], v[124:127]
	v_mfma_f32_16x16x32_bf16 v[116:119], v[136:139], v[144:147], v[116:119]
	v_mfma_f32_16x16x32_bf16 v[108:111], v[128:131], v[152:155], v[108:111]
	v_mfma_f32_16x16x32_bf16 v[100:103], v[136:139], v[152:155], v[100:103]
	v_mfma_f32_16x16x32_bf16 v[92:95], v[128:131], v[160:163], v[92:95]
	v_mfma_f32_16x16x32_bf16 v[84:87], v[136:139], v[160:163], v[84:87]
	v_mfma_f32_16x16x32_bf16 v[76:79], v[128:131], v[168:171], v[76:79]
	v_mfma_f32_16x16x32_bf16 v[68:71], v[136:139], v[168:171], v[68:71]
	v_mfma_f32_16x16x32_bf16 v[124:127], v[132:135], v[148:151], v[124:127]
	v_mfma_f32_16x16x32_bf16 v[116:119], v[140:143], v[148:151], v[116:119]
	v_mfma_f32_16x16x32_bf16 v[108:111], v[132:135], v[156:159], v[108:111]
	v_mfma_f32_16x16x32_bf16 v[100:103], v[140:143], v[156:159], v[100:103]
	v_mfma_f32_16x16x32_bf16 v[92:95], v[132:135], v[164:167], v[92:95]
	v_mfma_f32_16x16x32_bf16 v[84:87], v[140:143], v[164:167], v[84:87]
	v_mfma_f32_16x16x32_bf16 v[76:79], v[132:135], v[172:175], v[76:79]
	v_mfma_f32_16x16x32_bf16 v[68:71], v[140:143], v[172:175], v[68:71]
	v_mfma_f32_16x16x32_bf16 v[120:123], v[188:191], v[144:147], v[120:123]
	v_mfma_f32_16x16x32_bf16 v[112:115], v[200:203], v[144:147], v[112:115]
	v_mfma_f32_16x16x32_bf16 v[104:107], v[188:191], v[152:155], v[104:107]
	v_mfma_f32_16x16x32_bf16 v[96:99], v[200:203], v[152:155], v[96:99]
	v_mfma_f32_16x16x32_bf16 v[88:91], v[188:191], v[160:163], v[88:91]
	v_mfma_f32_16x16x32_bf16 v[80:83], v[200:203], v[160:163], v[80:83]
	v_mfma_f32_16x16x32_bf16 v[72:75], v[188:191], v[168:171], v[72:75]
	v_mfma_f32_16x16x32_bf16 v[64:67], v[200:203], v[168:171], v[64:67]
	v_mfma_f32_16x16x32_bf16 v[120:123], v[196:199], v[148:151], v[120:123]
	v_mfma_f32_16x16x32_bf16 v[112:115], v[218:221], v[148:151], v[112:115]
	v_mfma_f32_16x16x32_bf16 v[104:107], v[196:199], v[156:159], v[104:107]
	v_mfma_f32_16x16x32_bf16 v[96:99], v[218:221], v[156:159], v[96:99]
	v_mfma_f32_16x16x32_bf16 v[88:91], v[196:199], v[164:167], v[88:91]
	v_mfma_f32_16x16x32_bf16 v[80:83], v[218:221], v[164:167], v[80:83]
	v_mfma_f32_16x16x32_bf16 v[72:75], v[196:199], v[172:175], v[72:75]
	v_mfma_f32_16x16x32_bf16 v[64:67], v[218:221], v[172:175], v[64:67]
	s_barrier
	ds_read_b128 v[144:147], v216 offset:16384
	ds_read_b128 v[148:151], v216 offset:17408
	ds_read_b128 v[152:155], v216 offset:18432
	ds_read_b128 v[156:159], v216 offset:19456
	s_add_i32 m0, s92, 0x10000
	ds_read_b128 v[160:163], v216 offset:20480
	ds_read_b128 v[164:167], v216 offset:21504
	ds_read_b128 v[168:171], v216 offset:22528
	ds_read_b128 v[172:175], v216 offset:23552
	global_load_lds_dwordx4 v192, s[44:45]
	s_add_i32 m0, s92, 0x12000
	s_nop 0
	global_load_lds_dwordx4 v180, s[44:45]
	s_add_u32 s76, s44, 0x80000
	s_addc_u32 s77, s45, 0
	s_add_i32 m0, s92, 0x14000
	s_nop 0
	global_load_lds_dwordx4 v192, s[76:77]
	s_add_i32 m0, s92, 0x16000
	s_nop 0
	global_load_lds_dwordx4 v180, s[76:77]
	s_waitcnt vmcnt(4)
	s_waitcnt lgkmcnt(0)
	s_barrier
	v_mfma_f32_16x16x32_bf16 v[60:63], v[128:131], v[144:147], v[60:63]
	v_mfma_f32_16x16x32_bf16 v[52:55], v[136:139], v[144:147], v[52:55]
	v_mfma_f32_16x16x32_bf16 v[44:47], v[128:131], v[152:155], v[44:47]
	v_mfma_f32_16x16x32_bf16 v[36:39], v[136:139], v[152:155], v[36:39]
	v_mfma_f32_16x16x32_bf16 v[28:31], v[128:131], v[160:163], v[28:31]
	v_mfma_f32_16x16x32_bf16 v[20:23], v[136:139], v[160:163], v[20:23]
	v_mfma_f32_16x16x32_bf16 v[12:15], v[128:131], v[168:171], v[12:15]
	v_mfma_f32_16x16x32_bf16 v[4:7], v[136:139], v[168:171], v[4:7]
	v_mfma_f32_16x16x32_bf16 v[60:63], v[132:135], v[148:151], v[60:63]
	v_mfma_f32_16x16x32_bf16 v[52:55], v[140:143], v[148:151], v[52:55]
	v_mfma_f32_16x16x32_bf16 v[44:47], v[132:135], v[156:159], v[44:47]
	v_mfma_f32_16x16x32_bf16 v[36:39], v[140:143], v[156:159], v[36:39]
	v_mfma_f32_16x16x32_bf16 v[28:31], v[132:135], v[164:167], v[28:31]
	v_mfma_f32_16x16x32_bf16 v[20:23], v[140:143], v[164:167], v[20:23]
	v_mfma_f32_16x16x32_bf16 v[12:15], v[132:135], v[172:175], v[12:15]
	v_mfma_f32_16x16x32_bf16 v[4:7], v[140:143], v[172:175], v[4:7]
	v_mfma_f32_16x16x32_bf16 v[56:59], v[188:191], v[144:147], v[56:59]
	v_mfma_f32_16x16x32_bf16 v[48:51], v[200:203], v[144:147], v[48:51]
	v_mfma_f32_16x16x32_bf16 v[40:43], v[188:191], v[152:155], v[40:43]
	v_mfma_f32_16x16x32_bf16 v[32:35], v[200:203], v[152:155], v[32:35]
	v_mfma_f32_16x16x32_bf16 v[24:27], v[188:191], v[160:163], v[24:27]
	v_mfma_f32_16x16x32_bf16 v[16:19], v[200:203], v[160:163], v[16:19]
	v_mfma_f32_16x16x32_bf16 v[8:11], v[188:191], v[168:171], v[8:11]
	v_mfma_f32_16x16x32_bf16 v[0:3], v[200:203], v[168:171], v[0:3]
	v_mfma_f32_16x16x32_bf16 v[56:59], v[196:199], v[148:151], v[56:59]
	v_mfma_f32_16x16x32_bf16 v[48:51], v[218:221], v[148:151], v[48:51]
	v_mfma_f32_16x16x32_bf16 v[40:43], v[196:199], v[156:159], v[40:43]
	v_mfma_f32_16x16x32_bf16 v[32:35], v[218:221], v[156:159], v[32:35]
	v_mfma_f32_16x16x32_bf16 v[24:27], v[196:199], v[164:167], v[24:27]
	v_mfma_f32_16x16x32_bf16 v[16:19], v[218:221], v[164:167], v[16:19]
	v_mfma_f32_16x16x32_bf16 v[8:11], v[196:199], v[172:175], v[8:11]
	v_mfma_f32_16x16x32_bf16 v[0:3], v[218:221], v[172:175], v[0:3]
	s_barrier
; #define PG8_STAGE(bufoff, gbase, voff) do { _Pragma("unroll") for (int _i = 0; _i < 2; ++_i) \
;         __builtin_amdgcn_global_load_lds((const unsigned*)((const char*)(gbase) + (voff)[_i]), (LAS unsigned*)(lds + (bufoff) + ldsw + _i * 8192), 16, 0, 0); } while (0)
; #define PG8_LDA(dst, b, h) do { _Pragma("unroll") for (int m = 0; m < 4; ++m) _Pragma("unroll") for (int k = 0; k < 2; ++k) dst[m][k] = *(const LAS bf16x8*)(lds + PG8_SA(b, h) + aoff + m * 2048 + k * 1024); } while (0)
; #define PG8_LDB(dst, b, h) do { _Pragma("unroll") for (int n = 0; n < 2; ++n) _Pragma("unroll") for (int k = 0; k < 2; ++k) dst[n][k] = *(const LAS bf16x8*)(lds + PG8_SB(b, h) + boff + n * 2048 + k * 1024); } while (0)
; #define PG8_MMA(ai, bj, At, Bt) do { __builtin_amdgcn_s_setprio(1); _Pragma("unroll") for (int m = 0; m < 4; ++m) _Pragma("unroll") for (int n = 0; n < 2; ++n) _Pragma("unroll") for (int k = 0; k < 2; ++k) \
;         acc[ai][bj][m][n] = __builtin_amdgcn_mfma_f32_16x16x32_bf16(Bt[n][k], At[m][k], acc[ai][bj][m][n], 0, 0, 0); __builtin_amdgcn_s_setprio(0); } while (0)
; #define PG8_WAIT_V(n) asm volatile("s_waitcnt vmcnt(" #n ")" ::: "memory")
; #define PG8_WAIT_L(n) asm volatile("s_waitcnt lgkmcnt(" #n ")" ::: "memory")
; #define PG8_BAR __builtin_amdgcn_s_barrier()
; #define PG8_SCHED __builtin_amdgcn_sched_barrier(0)
; template <class Prog>
; __device__ __forceinline__ void gemm_phase(LAS unsigned char* lds, const int K, const Prog& S) {
;     ...
;             PG8_LDB(B0, 1, 0); PG8_SCHED; PG8_LDA(At, 1, 0); PG8_STAGE(PG8_SA(0, 1), a2 + hstep, voffA);
;             PG8_WAIT_L(8); PG8_BAR; PG8_WAIT_L(0); PG8_MMA(0, 0, At, B0); PG8_BAR; PG8_SCHED;
;             PG8_LDB(B1, 1, 1); PG8_STAGE(PG8_SB(1, 0), b3, voffB);
;             PG8_BAR; PG8_WAIT_L(0); PG8_MMA(0, 1, At, B1); PG8_BAR;
;             PG8_LDA(At, 1, 1); PG8_STAGE(PG8_SA(1, 0), a3, voffA);
;             PG8_BAR; PG8_WAIT_L(0); PG8_MMA(1, 0, At, B0); PG8_BAR; PG8_SCHED;
;             PG8_STAGE(PG8_SB(1, 1), b3 + hstep, voffB);
;             PG8_WAIT_V(6); PG8_BAR; PG8_MMA(1, 1, At, B1); PG8_BAR;
;     __device__ __forceinline__ void epi(f32x4 (&acc)[2][2][4][2], const pg8::Unit& u, int wr, int wc, int fr, int fq) const {
;     ...
;         const int mode = (pn < 8) ? 1 : ((pn >= 12 && pn < 16) || (pn >= 20 && pn < 24) || (pn >= 30 && pn < 34)) ? 2 : (pn >= 34 ? 3 : 0);
	s_add_u32 s76, s46, 0x80000
	s_addc_u32 s77, s47, 0
	ds_read_b128 v[128:131], v244 offset:32768
	ds_read_b128 v[132:135], v244 offset:33792
	ds_read_b128 v[136:139], v244 offset:34816
	ds_read_b128 v[140:143], v244 offset:35840
	s_mov_b32 m0, s92
	ds_read_b128 v[188:191], v244 offset:49152
	ds_read_b128 v[196:199], v244 offset:50176
	ds_read_b128 v[200:203], v244 offset:51200
	ds_read_b128 v[218:221], v244 offset:52224
	global_load_lds_dwordx4 v176, s[46:47]
	s_add_i32 m0, s92, 0x2000
	ds_read_b128 v[144:147], v216 offset:32768
	ds_read_b128 v[148:151], v216 offset:33792
	ds_read_b128 v[152:155], v216 offset:34816
	ds_read_b128 v[156:159], v216 offset:35840
	global_load_lds_dwordx4 v178, s[46:47]
	s_add_i32 m0, s92, 0x4000
	ds_read_b128 v[160:163], v216 offset:36864
	ds_read_b128 v[164:167], v216 offset:37888
	ds_read_b128 v[168:171], v216 offset:38912
	ds_read_b128 v[172:175], v216 offset:39936
	global_load_lds_dwordx4 v176, s[76:77]
	s_add_i32 m0, s92, 0x6000
	s_nop 0
	global_load_lds_dwordx4 v178, s[76:77]
	s_waitcnt lgkmcnt(0)
	s_barrier
	v_mfma_f32_16x16x32_bf16 v[124:127], v[128:131], v[144:147], v[124:127]
	v_mfma_f32_16x16x32_bf16 v[116:119], v[136:139], v[144:147], v[116:119]
	v_mfma_f32_16x16x32_bf16 v[108:111], v[128:131], v[152:155], v[108:111]
	v_mfma_f32_16x16x32_bf16 v[100:103], v[136:139], v[152:155], v[100:103]
	v_mfma_f32_16x16x32_bf16 v[92:95], v[128:131], v[160:163], v[92:95]
	v_mfma_f32_16x16x32_bf16 v[84:87], v[136:139], v[160:163], v[84:87]
	v_mfma_f32_16x16x32_bf16 v[76:79], v[128:131], v[168:171], v[76:79]
	v_mfma_f32_16x16x32_bf16 v[68:71], v[136:139], v[168:171], v[68:71]
	v_mfma_f32_16x16x32_bf16 v[124:127], v[132:135], v[148:151], v[124:127]
	v_mfma_f32_16x16x32_bf16 v[116:119], v[140:143], v[148:151], v[116:119]
	v_mfma_f32_16x16x32_bf16 v[108:111], v[132:135], v[156:159], v[108:111]
	v_mfma_f32_16x16x32_bf16 v[100:103], v[140:143], v[156:159], v[100:103]
	v_mfma_f32_16x16x32_bf16 v[92:95], v[132:135], v[164:167], v[92:95]
	v_mfma_f32_16x16x32_bf16 v[84:87], v[140:143], v[164:167], v[84:87]
	v_mfma_f32_16x16x32_bf16 v[76:79], v[132:135], v[172:175], v[76:79]
	v_mfma_f32_16x16x32_bf16 v[68:71], v[140:143], v[172:175], v[68:71]
	v_mfma_f32_16x16x32_bf16 v[120:123], v[188:191], v[144:147], v[120:123]
	v_mfma_f32_16x16x32_bf16 v[112:115], v[200:203], v[144:147], v[112:115]
	v_mfma_f32_16x16x32_bf16 v[104:107], v[188:191], v[152:155], v[104:107]
	v_mfma_f32_16x16x32_bf16 v[96:99], v[200:203], v[152:155], v[96:99]
	v_mfma_f32_16x16x32_bf16 v[88:91], v[188:191], v[160:163], v[88:91]
	v_mfma_f32_16x16x32_bf16 v[80:83], v[200:203], v[160:163], v[80:83]
	v_mfma_f32_16x16x32_bf16 v[72:75], v[188:191], v[168:171], v[72:75]
	v_mfma_f32_16x16x32_bf16 v[64:67], v[200:203], v[168:171], v[64:67]
	v_mfma_f32_16x16x32_bf16 v[120:123], v[196:199], v[148:151], v[120:123]
	v_mfma_f32_16x16x32_bf16 v[112:115], v[218:221], v[148:151], v[112:115]
	v_mfma_f32_16x16x32_bf16 v[104:107], v[196:199], v[156:159], v[104:107]
	v_mfma_f32_16x16x32_bf16 v[96:99], v[218:221], v[156:159], v[96:99]
	v_mfma_f32_16x16x32_bf16 v[88:91], v[196:199], v[164:167], v[88:91]
	v_mfma_f32_16x16x32_bf16 v[80:83], v[218:221], v[164:167], v[80:83]
	v_mfma_f32_16x16x32_bf16 v[72:75], v[196:199], v[172:175], v[72:75]
	v_mfma_f32_16x16x32_bf16 v[64:67], v[218:221], v[172:175], v[64:67]
	s_nop 0
	s_barrier
	s_add_u32 s76, s44, 0x80
	s_addc_u32 s77, s45, 0
	ds_read_b128 v[144:147], v216 offset:49152
	ds_read_b128 v[148:151], v216 offset:50176
	ds_read_b128 v[152:155], v216 offset:51200
	ds_read_b128 v[156:159], v216 offset:52224
	s_add_i32 m0, s92, 0x18000
	ds_read_b128 v[160:163], v216 offset:53248
	ds_read_b128 v[164:167], v216 offset:54272
	ds_read_b128 v[168:171], v216 offset:55296
	ds_read_b128 v[172:175], v216 offset:56320
	global_load_lds_dwordx4 v192, s[76:77]
	s_add_i32 m0, s92, 0x1a000
	s_nop 0
	global_load_lds_dwordx4 v180, s[76:77]
	s_add_u32 s76, s44, 0x80080
	s_addc_u32 s77, s45, 0
	s_add_i32 m0, s92, 0x1c000
	s_nop 0
	global_load_lds_dwordx4 v192, s[76:77]
	s_add_i32 m0, s92, 0x1e000
	s_nop 0
	global_load_lds_dwordx4 v180, s[76:77]
	s_waitcnt vmcnt(4)
	s_waitcnt lgkmcnt(0)
	s_barrier
	v_mfma_f32_16x16x32_bf16 v[60:63], v[128:131], v[144:147], v[60:63]
	v_mfma_f32_16x16x32_bf16 v[52:55], v[136:139], v[144:147], v[52:55]
	v_mfma_f32_16x16x32_bf16 v[44:47], v[128:131], v[152:155], v[44:47]
	v_mfma_f32_16x16x32_bf16 v[36:39], v[136:139], v[152:155], v[36:39]
	v_mfma_f32_16x16x32_bf16 v[28:31], v[128:131], v[160:163], v[28:31]
	v_mfma_f32_16x16x32_bf16 v[20:23], v[136:139], v[160:163], v[20:23]
	v_mfma_f32_16x16x32_bf16 v[12:15], v[128:131], v[168:171], v[12:15]
	v_mfma_f32_16x16x32_bf16 v[4:7], v[136:139], v[168:171], v[4:7]
	v_mfma_f32_16x16x32_bf16 v[60:63], v[132:135], v[148:151], v[60:63]
	v_mfma_f32_16x16x32_bf16 v[52:55], v[140:143], v[148:151], v[52:55]
	v_mfma_f32_16x16x32_bf16 v[44:47], v[132:135], v[156:159], v[44:47]
	v_mfma_f32_16x16x32_bf16 v[36:39], v[140:143], v[156:159], v[36:39]
	v_mfma_f32_16x16x32_bf16 v[28:31], v[132:135], v[164:167], v[28:31]
	v_mfma_f32_16x16x32_bf16 v[20:23], v[140:143], v[164:167], v[20:23]
	v_mfma_f32_16x16x32_bf16 v[12:15], v[132:135], v[172:175], v[12:15]
	v_mfma_f32_16x16x32_bf16 v[4:7], v[140:143], v[172:175], v[4:7]
	v_mfma_f32_16x16x32_bf16 v[56:59], v[188:191], v[144:147], v[56:59]
	v_mfma_f32_16x16x32_bf16 v[48:51], v[200:203], v[144:147], v[48:51]
	v_mfma_f32_16x16x32_bf16 v[40:43], v[188:191], v[152:155], v[40:43]
	v_mfma_f32_16x16x32_bf16 v[32:35], v[200:203], v[152:155], v[32:35]
	v_mfma_f32_16x16x32_bf16 v[24:27], v[188:191], v[160:163], v[24:27]
	v_mfma_f32_16x16x32_bf16 v[16:19], v[200:203], v[160:163], v[16:19]
	v_mfma_f32_16x16x32_bf16 v[8:11], v[188:191], v[168:171], v[8:11]
	v_mfma_f32_16x16x32_bf16 v[0:3], v[200:203], v[168:171], v[0:3]
	v_mfma_f32_16x16x32_bf16 v[56:59], v[196:199], v[148:151], v[56:59]
	v_mfma_f32_16x16x32_bf16 v[48:51], v[218:221], v[148:151], v[48:51]
	v_mfma_f32_16x16x32_bf16 v[40:43], v[196:199], v[156:159], v[40:43]
	v_mfma_f32_16x16x32_bf16 v[32:35], v[218:221], v[156:159], v[32:35]
	v_mfma_f32_16x16x32_bf16 v[24:27], v[196:199], v[164:167], v[24:27]
	v_mfma_f32_16x16x32_bf16 v[16:19], v[218:221], v[164:167], v[16:19]
	v_mfma_f32_16x16x32_bf16 v[8:11], v[196:199], v[172:175], v[8:11]
	v_mfma_f32_16x16x32_bf16 v[0:3], v[218:221], v[172:175], v[0:3]
	s_add_i32 s69, s69, 2
	s_add_u32 s40, s40, 0x100
	s_addc_u32 s41, s41, 0
	s_add_u32 s9, s9, 0x100
	s_addc_u32 s15, s15, 0
	s_cmp_gt_u32 s69, 29
	s_barrier
	s_cbranch_scc0 .LBB0_101
	s_cmp_lt_i32 s75, 8
	s_mov_b32 s9, 1
	s_cbranch_scc1 .LBB0_110
	s_sub_i32 s4, s75, 30
	s_cmp_lt_u32 s4, 4
	s_mov_b32 s9, 2
	s_cbranch_scc1 .LBB0_110
	s_and_b32 s9, s75, 0x7ffffffc
	s_cmp_lt_i32 s9, 20
	s_cbranch_scc1 .LBB0_106
	s_cmp_lg_u32 s9, 20
	s_cselect_b64 s[4:5], -1, 0
	s_cbranch_execz .LBB0_107
	s_branch .LBB0_108

; #define PG8_STAGE(bufoff, gbase, voff) do { _Pragma("unroll") for (int _i = 0; _i < 2; ++_i) \
;         __builtin_amdgcn_global_load_lds((const unsigned*)((const char*)(gbase) + (voff)[_i]), (LAS unsigned*)(lds + (bufoff) + ldsw + _i * 8192), 16, 0, 0); } while (0)
; #define PG8_LDA(dst, b, h) do { _Pragma("unroll") for (int m = 0; m < 4; ++m) _Pragma("unroll") for (int k = 0; k < 2; ++k) dst[m][k] = *(const LAS bf16x8*)(lds + PG8_SA(b, h) + aoff + m * 2048 + k * 1024); } while (0)
; #define PG8_LDB(dst, b, h) do { _Pragma("unroll") for (int n = 0; n < 2; ++n) _Pragma("unroll") for (int k = 0; k < 2; ++k) dst[n][k] = *(const LAS bf16x8*)(lds + PG8_SB(b, h) + boff + n * 2048 + k * 1024); } while (0)
; #define PG8_MMA(ai, bj, At, Bt) do { __builtin_amdgcn_s_setprio(1); _Pragma("unroll") for (int m = 0; m < 4; ++m) _Pragma("unroll") for (int n = 0; n < 2; ++n) _Pragma("unroll") for (int k = 0; k < 2; ++k) \
;         acc[ai][bj][m][n] = __builtin_amdgcn_mfma_f32_16x16x32_bf16(Bt[n][k], At[m][k], acc[ai][bj][m][n], 0, 0, 0); __builtin_amdgcn_s_setprio(0); } while (0)
; #define PG8_WAIT_V(n) asm volatile("s_waitcnt vmcnt(" #n ")" ::: "memory")
; #define PG8_WAIT_L(n) asm volatile("s_waitcnt lgkmcnt(" #n ")" ::: "memory")
; #define PG8_BAR __builtin_amdgcn_s_barrier()
; #define PG8_SCHED __builtin_amdgcn_sched_barrier(0)
; template <class Prog>
; __device__ __forceinline__ void gemm_phase(LAS unsigned char* lds, const int K, const Prog& S) {
;     ...
;             PG8_LDB(B0, 0, 0); PG8_SCHED; PG8_LDA(At, 0, 0); PG8_STAGE(PG8_SA(1, 1), a1 + hstep, voffA);
;             PG8_WAIT_L(8); PG8_BAR; PG8_WAIT_L(0); PG8_MMA(0, 0, At, B0); PG8_BAR; PG8_SCHED;
;             PG8_LDB(B1, 0, 1); PG8_STAGE(PG8_SB(0, 0), b2, voffB);
;             PG8_BAR; PG8_WAIT_L(0); PG8_MMA(0, 1, At, B1); PG8_BAR;
;             PG8_LDA(At, 0, 1); PG8_STAGE(PG8_SA(0, 0), a2, voffA);
;             PG8_BAR; PG8_WAIT_L(0); PG8_MMA(1, 0, At, B0); PG8_BAR; PG8_SCHED;
;             PG8_STAGE(PG8_SB(0, 1), b2 + hstep, voffB);
;             PG8_WAIT_V(6); PG8_BAR; PG8_MMA(1, 1, At, B1); PG8_BAR;
.LBB0_400:
	s_add_u32 s46, s44, 0xfffc0080
	s_addc_u32 s47, s45, -1
	s_cmp_eq_u32 s55, 12
	s_cselect_b32 s53, s7, s47
	s_cselect_b32 s52, s6, s46
	s_cselect_b32 s47, s9, s43
	s_cselect_b32 s46, s8, s41
	s_add_u32 s84, s44, 0xfffc0000
	s_addc_u32 s85, s45, -1
	ds_read_b128 v[128:131], v206
	ds_read_b128 v[132:135], v206 offset:1024
	ds_read_b128 v[136:139], v206 offset:2048
	ds_read_b128 v[140:143], v206 offset:3072
	s_add_i32 m0, s74, 0x8000
	ds_read_b128 v[176:179], v206 offset:16384
	ds_read_b128 v[180:183], v206 offset:17408
	ds_read_b128 v[184:187], v206 offset:18432
	ds_read_b128 v[188:191], v206 offset:19456
	global_load_lds_dwordx4 v202, s[84:85]
	s_add_i32 m0, s74, 0xa000
	ds_read_b128 v[144:147], v247
	ds_read_b128 v[148:151], v247 offset:1024
	ds_read_b128 v[152:155], v247 offset:2048
	ds_read_b128 v[156:159], v247 offset:3072
	global_load_lds_dwordx4 v204, s[84:85]
	s_add_i32 m0, s74, 0xc000
	ds_read_b128 v[160:163], v247 offset:4096
	ds_read_b128 v[164:167], v247 offset:5120
	ds_read_b128 v[168:171], v247 offset:6144
	ds_read_b128 v[172:175], v247 offset:7168
	global_load_lds_dwordx4 v202, s[44:45]
	s_add_i32 m0, s74, 0xe000
	s_nop 0
	global_load_lds_dwordx4 v204, s[44:45]
	s_waitcnt lgkmcnt(0)
	s_barrier
	v_mfma_f32_16x16x32_bf16 v[124:127], v[128:131], v[144:147], v[124:127]
	v_mfma_f32_16x16x32_bf16 v[120:123], v[136:139], v[144:147], v[120:123]
	v_mfma_f32_16x16x32_bf16 v[116:119], v[128:131], v[152:155], v[116:119]
	v_mfma_f32_16x16x32_bf16 v[112:115], v[136:139], v[152:155], v[112:115]
	v_mfma_f32_16x16x32_bf16 v[108:111], v[128:131], v[160:163], v[108:111]
	v_mfma_f32_16x16x32_bf16 v[104:107], v[136:139], v[160:163], v[104:107]
	v_mfma_f32_16x16x32_bf16 v[100:103], v[128:131], v[168:171], v[100:103]
	v_mfma_f32_16x16x32_bf16 v[96:99], v[136:139], v[168:171], v[96:99]
	v_mfma_f32_16x16x32_bf16 v[124:127], v[132:135], v[148:151], v[124:127]
	v_mfma_f32_16x16x32_bf16 v[120:123], v[140:143], v[148:151], v[120:123]
	v_mfma_f32_16x16x32_bf16 v[116:119], v[132:135], v[156:159], v[116:119]
	v_mfma_f32_16x16x32_bf16 v[112:115], v[140:143], v[156:159], v[112:115]
	v_mfma_f32_16x16x32_bf16 v[108:111], v[132:135], v[164:167], v[108:111]
	v_mfma_f32_16x16x32_bf16 v[104:107], v[140:143], v[164:167], v[104:107]
	v_mfma_f32_16x16x32_bf16 v[100:103], v[132:135], v[172:175], v[100:103]
	v_mfma_f32_16x16x32_bf16 v[96:99], v[140:143], v[172:175], v[96:99]
	v_mfma_f32_16x16x32_bf16 v[92:95], v[176:179], v[144:147], v[92:95]
	v_mfma_f32_16x16x32_bf16 v[88:91], v[184:187], v[144:147], v[88:91]
	v_mfma_f32_16x16x32_bf16 v[84:87], v[176:179], v[152:155], v[84:87]
	v_mfma_f32_16x16x32_bf16 v[80:83], v[184:187], v[152:155], v[80:83]
	v_mfma_f32_16x16x32_bf16 v[76:79], v[176:179], v[160:163], v[76:79]
	v_mfma_f32_16x16x32_bf16 v[72:75], v[184:187], v[160:163], v[72:75]
	v_mfma_f32_16x16x32_bf16 v[68:71], v[176:179], v[168:171], v[68:71]
	v_mfma_f32_16x16x32_bf16 v[64:67], v[184:187], v[168:171], v[64:67]
	v_mfma_f32_16x16x32_bf16 v[92:95], v[180:183], v[148:151], v[92:95]
	v_mfma_f32_16x16x32_bf16 v[88:91], v[188:191], v[148:151], v[88:91]
	v_mfma_f32_16x16x32_bf16 v[84:87], v[180:183], v[156:159], v[84:87]
	v_mfma_f32_16x16x32_bf16 v[80:83], v[188:191], v[156:159], v[80:83]
	v_mfma_f32_16x16x32_bf16 v[76:79], v[180:183], v[164:167], v[76:79]
	v_mfma_f32_16x16x32_bf16 v[72:75], v[188:191], v[164:167], v[72:75]
	v_mfma_f32_16x16x32_bf16 v[68:71], v[180:183], v[172:175], v[68:71]
	v_mfma_f32_16x16x32_bf16 v[64:67], v[188:191], v[172:175], v[64:67]
	s_barrier
	ds_read_b128 v[144:147], v247 offset:16384
	ds_read_b128 v[148:151], v247 offset:17408
	ds_read_b128 v[152:155], v247 offset:18432
	ds_read_b128 v[156:159], v247 offset:19456
	s_add_i32 m0, s74, 0x10000
	ds_read_b128 v[160:163], v247 offset:20480
	ds_read_b128 v[164:167], v247 offset:21504
	ds_read_b128 v[168:171], v247 offset:22528
	ds_read_b128 v[172:175], v247 offset:23552
	global_load_lds_dwordx4 v192, s[46:47]
	s_add_i32 m0, s74, 0x12000
	s_nop 0
	global_load_lds_dwordx4 v200, s[46:47]
	s_add_u32 s84, s46, 0x40000
	s_addc_u32 s85, s47, 0
	s_add_i32 m0, s74, 0x14000
	s_nop 0
	global_load_lds_dwordx4 v192, s[84:85]
	s_add_i32 m0, s74, 0x16000
	s_nop 0
	global_load_lds_dwordx4 v200, s[84:85]
	s_waitcnt vmcnt(4)
	s_waitcnt lgkmcnt(0)
	s_barrier
	v_mfma_f32_16x16x32_bf16 v[60:63], v[128:131], v[144:147], v[60:63]
	v_mfma_f32_16x16x32_bf16 v[56:59], v[136:139], v[144:147], v[56:59]
	v_mfma_f32_16x16x32_bf16 v[52:55], v[128:131], v[152:155], v[52:55]
	v_mfma_f32_16x16x32_bf16 v[48:51], v[136:139], v[152:155], v[48:51]
	v_mfma_f32_16x16x32_bf16 v[44:47], v[128:131], v[160:163], v[44:47]
	v_mfma_f32_16x16x32_bf16 v[40:43], v[136:139], v[160:163], v[40:43]
	v_mfma_f32_16x16x32_bf16 v[36:39], v[128:131], v[168:171], v[36:39]
	v_mfma_f32_16x16x32_bf16 v[32:35], v[136:139], v[168:171], v[32:35]
	v_mfma_f32_16x16x32_bf16 v[60:63], v[132:135], v[148:151], v[60:63]
	v_mfma_f32_16x16x32_bf16 v[56:59], v[140:143], v[148:151], v[56:59]
	v_mfma_f32_16x16x32_bf16 v[52:55], v[132:135], v[156:159], v[52:55]
	v_mfma_f32_16x16x32_bf16 v[48:51], v[140:143], v[156:159], v[48:51]
	v_mfma_f32_16x16x32_bf16 v[44:47], v[132:135], v[164:167], v[44:47]
	v_mfma_f32_16x16x32_bf16 v[40:43], v[140:143], v[164:167], v[40:43]
	v_mfma_f32_16x16x32_bf16 v[36:39], v[132:135], v[172:175], v[36:39]
	v_mfma_f32_16x16x32_bf16 v[32:35], v[140:143], v[172:175], v[32:35]
	v_mfma_f32_16x16x32_bf16 v[28:31], v[176:179], v[144:147], v[28:31]
	v_mfma_f32_16x16x32_bf16 v[24:27], v[184:187], v[144:147], v[24:27]
	v_mfma_f32_16x16x32_bf16 v[20:23], v[176:179], v[152:155], v[20:23]
	v_mfma_f32_16x16x32_bf16 v[16:19], v[184:187], v[152:155], v[16:19]
	v_mfma_f32_16x16x32_bf16 v[12:15], v[176:179], v[160:163], v[12:15]
	v_mfma_f32_16x16x32_bf16 v[8:11], v[184:187], v[160:163], v[8:11]
	v_mfma_f32_16x16x32_bf16 v[4:7], v[176:179], v[168:171], v[4:7]
	v_mfma_f32_16x16x32_bf16 v[0:3], v[184:187], v[168:171], v[0:3]
	v_mfma_f32_16x16x32_bf16 v[28:31], v[180:183], v[148:151], v[28:31]
	v_mfma_f32_16x16x32_bf16 v[24:27], v[188:191], v[148:151], v[24:27]
	v_mfma_f32_16x16x32_bf16 v[20:23], v[180:183], v[156:159], v[20:23]
	v_mfma_f32_16x16x32_bf16 v[16:19], v[188:191], v[156:159], v[16:19]
	v_mfma_f32_16x16x32_bf16 v[12:15], v[180:183], v[164:167], v[12:15]
	v_mfma_f32_16x16x32_bf16 v[8:11], v[188:191], v[164:167], v[8:11]
	v_mfma_f32_16x16x32_bf16 v[4:7], v[180:183], v[172:175], v[4:7]
	v_mfma_f32_16x16x32_bf16 v[0:3], v[188:191], v[172:175], v[0:3]
	s_barrier
; #define PG8_STAGE(bufoff, gbase, voff) do { _Pragma("unroll") for (int _i = 0; _i < 2; ++_i) \
;         __builtin_amdgcn_global_load_lds((const unsigned*)((const char*)(gbase) + (voff)[_i]), (LAS unsigned*)(lds + (bufoff) + ldsw + _i * 8192), 16, 0, 0); } while (0)
; #define PG8_LDA(dst, b, h) do { _Pragma("unroll") for (int m = 0; m < 4; ++m) _Pragma("unroll") for (int k = 0; k < 2; ++k) dst[m][k] = *(const LAS bf16x8*)(lds + PG8_SA(b, h) + aoff + m * 2048 + k * 1024); } while (0)
; #define PG8_LDB(dst, b, h) do { _Pragma("unroll") for (int n = 0; n < 2; ++n) _Pragma("unroll") for (int k = 0; k < 2; ++k) dst[n][k] = *(const LAS bf16x8*)(lds + PG8_SB(b, h) + boff + n * 2048 + k * 1024); } while (0)
; #define PG8_MMA(ai, bj, At, Bt) do { __builtin_amdgcn_s_setprio(1); _Pragma("unroll") for (int m = 0; m < 4; ++m) _Pragma("unroll") for (int n = 0; n < 2; ++n) _Pragma("unroll") for (int k = 0; k < 2; ++k) \
;         acc[ai][bj][m][n] = __builtin_amdgcn_mfma_f32_16x16x32_bf16(Bt[n][k], At[m][k], acc[ai][bj][m][n], 0, 0, 0); __builtin_amdgcn_s_setprio(0); } while (0)
; #define PG8_WAIT_L(n) asm volatile("s_waitcnt lgkmcnt(" #n ")" ::: "memory")
; #define PG8_BAR __builtin_amdgcn_s_barrier()
; #define PG8_SCHED __builtin_amdgcn_sched_barrier(0)
; template <class Prog>
; __device__ __forceinline__ void gemm_phase(LAS unsigned char* lds, const int K, const Prog& S) {
;     ...
;             PG8_LDB(B0, 1, 0); PG8_SCHED; PG8_LDA(At, 1, 0); PG8_STAGE(PG8_SA(0, 1), a2 + hstep, voffA);
;             PG8_WAIT_L(8); PG8_BAR; PG8_WAIT_L(0); PG8_MMA(0, 0, At, B0); PG8_BAR; PG8_SCHED;
	s_add_u32 s84, s52, 0x40000
	s_addc_u32 s85, s53, 0
	ds_read_b128 v[128:131], v206 offset:32768
	ds_read_b128 v[132:135], v206 offset:33792
	ds_read_b128 v[136:139], v206 offset:34816
	ds_read_b128 v[140:143], v206 offset:35840
	s_mov_b32 m0, s74
	ds_read_b128 v[176:179], v206 offset:49152
	ds_read_b128 v[180:183], v206 offset:50176
	ds_read_b128 v[184:187], v206 offset:51200
	ds_read_b128 v[188:191], v206 offset:52224
	global_load_lds_dwordx4 v196, s[52:53]
	s_add_i32 m0, s74, 0x2000
	ds_read_b128 v[144:147], v247 offset:32768
	ds_read_b128 v[148:151], v247 offset:33792
	ds_read_b128 v[152:155], v247 offset:34816
	ds_read_b128 v[156:159], v247 offset:35840
	global_load_lds_dwordx4 v198, s[52:53]
	s_add_i32 m0, s74, 0x4000
	ds_read_b128 v[160:163], v247 offset:36864
	ds_read_b128 v[164:167], v247 offset:37888
	ds_read_b128 v[168:171], v247 offset:38912
	ds_read_b128 v[172:175], v247 offset:39936
	global_load_lds_dwordx4 v196, s[84:85]
	s_add_i32 m0, s74, 0x6000
	s_nop 0
	global_load_lds_dwordx4 v198, s[84:85]
	s_waitcnt lgkmcnt(0)
	s_barrier
	v_mfma_f32_16x16x32_bf16 v[124:127], v[128:131], v[144:147], v[124:127]
	v_mfma_f32_16x16x32_bf16 v[120:123], v[136:139], v[144:147], v[120:123]
	v_mfma_f32_16x16x32_bf16 v[116:119], v[128:131], v[152:155], v[116:119]
	v_mfma_f32_16x16x32_bf16 v[112:115], v[136:139], v[152:155], v[112:115]
	v_mfma_f32_16x16x32_bf16 v[108:111], v[128:131], v[160:163], v[108:111]
	v_mfma_f32_16x16x32_bf16 v[104:107], v[136:139], v[160:163], v[104:107]
	v_mfma_f32_16x16x32_bf16 v[100:103], v[128:131], v[168:171], v[100:103]
	v_mfma_f32_16x16x32_bf16 v[96:99], v[136:139], v[168:171], v[96:99]
	v_mfma_f32_16x16x32_bf16 v[124:127], v[132:135], v[148:151], v[124:127]
	v_mfma_f32_16x16x32_bf16 v[120:123], v[140:143], v[148:151], v[120:123]
	v_mfma_f32_16x16x32_bf16 v[116:119], v[132:135], v[156:159], v[116:119]
	v_mfma_f32_16x16x32_bf16 v[112:115], v[140:143], v[156:159], v[112:115]
	v_mfma_f32_16x16x32_bf16 v[108:111], v[132:135], v[164:167], v[108:111]
	v_mfma_f32_16x16x32_bf16 v[104:107], v[140:143], v[164:167], v[104:107]
	v_mfma_f32_16x16x32_bf16 v[100:103], v[132:135], v[172:175], v[100:103]
	v_mfma_f32_16x16x32_bf16 v[96:99], v[140:143], v[172:175], v[96:99]
	v_mfma_f32_16x16x32_bf16 v[92:95], v[176:179], v[144:147], v[92:95]
	v_mfma_f32_16x16x32_bf16 v[88:91], v[184:187], v[144:147], v[88:91]
	v_mfma_f32_16x16x32_bf16 v[84:87], v[176:179], v[152:155], v[84:87]
	v_mfma_f32_16x16x32_bf16 v[80:83], v[184:187], v[152:155], v[80:83]
	v_mfma_f32_16x16x32_bf16 v[76:79], v[176:179], v[160:163], v[76:79]
	v_mfma_f32_16x16x32_bf16 v[72:75], v[184:187], v[160:163], v[72:75]
	v_mfma_f32_16x16x32_bf16 v[68:71], v[176:179], v[168:171], v[68:71]
	v_mfma_f32_16x16x32_bf16 v[64:67], v[184:187], v[168:171], v[64:67]
	v_mfma_f32_16x16x32_bf16 v[92:95], v[180:183], v[148:151], v[92:95]
	v_mfma_f32_16x16x32_bf16 v[88:91], v[188:191], v[148:151], v[88:91]
	v_mfma_f32_16x16x32_bf16 v[84:87], v[180:183], v[156:159], v[84:87]
	v_mfma_f32_16x16x32_bf16 v[80:83], v[188:191], v[156:159], v[80:83]
	v_mfma_f32_16x16x32_bf16 v[76:79], v[180:183], v[164:167], v[76:79]
	v_mfma_f32_16x16x32_bf16 v[72:75], v[188:191], v[164:167], v[72:75]
	v_mfma_f32_16x16x32_bf16 v[68:71], v[180:183], v[172:175], v[68:71]
	v_mfma_f32_16x16x32_bf16 v[64:67], v[188:191], v[172:175], v[64:67]
	s_nop 0
	s_barrier
; #define PG8_STAGE(bufoff, gbase, voff) do { _Pragma("unroll") for (int _i = 0; _i < 2; ++_i) \
;         __builtin_amdgcn_global_load_lds((const unsigned*)((const char*)(gbase) + (voff)[_i]), (LAS unsigned*)(lds + (bufoff) + ldsw + _i * 8192), 16, 0, 0); } while (0)
; #define PG8_LDA(dst, b, h) do { _Pragma("unroll") for (int m = 0; m < 4; ++m) _Pragma("unroll") for (int k = 0; k < 2; ++k) dst[m][k] = *(const LAS bf16x8*)(lds + PG8_SA(b, h) + aoff + m * 2048 + k * 1024); } while (0)
; #define PG8_LDB(dst, b, h) do { _Pragma("unroll") for (int n = 0; n < 2; ++n) _Pragma("unroll") for (int k = 0; k < 2; ++k) dst[n][k] = *(const LAS bf16x8*)(lds + PG8_SB(b, h) + boff + n * 2048 + k * 1024); } while (0)
; #define PG8_MMA(ai, bj, At, Bt) do { __builtin_amdgcn_s_setprio(1); _Pragma("unroll") for (int m = 0; m < 4; ++m) _Pragma("unroll") for (int n = 0; n < 2; ++n) _Pragma("unroll") for (int k = 0; k < 2; ++k) \
;         acc[ai][bj][m][n] = __builtin_amdgcn_mfma_f32_16x16x32_bf16(Bt[n][k], At[m][k], acc[ai][bj][m][n], 0, 0, 0); __builtin_amdgcn_s_setprio(0); } while (0)
; #define PG8_WAIT_V(n) asm volatile("s_waitcnt vmcnt(" #n ")" ::: "memory")
; #define PG8_WAIT_L(n) asm volatile("s_waitcnt lgkmcnt(" #n ")" ::: "memory")
; #define PG8_BAR __builtin_amdgcn_s_barrier()
; #define PG8_SCHED __builtin_amdgcn_sched_barrier(0)
; template <class Prog>
; __device__ __forceinline__ void gemm_phase(LAS unsigned char* lds, const int K, const Prog& S) {
;     ...
;             PG8_LDB(B1, 1, 1); PG8_STAGE(PG8_SB(1, 0), b3, voffB);
;             PG8_BAR; PG8_WAIT_L(0); PG8_MMA(0, 1, At, B1); PG8_BAR;
;             PG8_LDA(At, 1, 1); PG8_STAGE(PG8_SA(1, 0), a3, voffA);
;             PG8_BAR; PG8_WAIT_L(0); PG8_MMA(1, 0, At, B0); PG8_BAR; PG8_SCHED;
;             PG8_STAGE(PG8_SB(1, 1), b3 + hstep, voffB);
;             PG8_WAIT_V(6); PG8_BAR; PG8_MMA(1, 1, At, B1); PG8_BAR;
;     __device__ __forceinline__ void epi(f32x4 (&acc)[2][2][4][2], const pg8::Unit& u, int wr, int wc, int fr, int fq) const {
;     ...
;         u32x4 gn[4][2][2], gd[4][2][2];
;         const int dsub = sub < 2 ? sub + 1 : sub;
	s_add_u32 s84, s46, 0x80
	s_addc_u32 s85, s47, 0
	ds_read_b128 v[144:147], v247 offset:49152
	ds_read_b128 v[148:151], v247 offset:50176
	ds_read_b128 v[152:155], v247 offset:51200
	ds_read_b128 v[156:159], v247 offset:52224
	s_add_i32 m0, s74, 0x18000
	ds_read_b128 v[160:163], v247 offset:53248
	ds_read_b128 v[164:167], v247 offset:54272
	ds_read_b128 v[168:171], v247 offset:55296
	ds_read_b128 v[172:175], v247 offset:56320
	global_load_lds_dwordx4 v192, s[84:85]
	s_add_i32 m0, s74, 0x1a000
	s_nop 0
	global_load_lds_dwordx4 v200, s[84:85]
	s_add_u32 s84, s46, 0x40080
	s_addc_u32 s85, s47, 0
	s_add_i32 m0, s74, 0x1c000
	s_nop 0
	global_load_lds_dwordx4 v192, s[84:85]
	s_add_i32 m0, s74, 0x1e000
	s_nop 0
	global_load_lds_dwordx4 v200, s[84:85]
	s_waitcnt vmcnt(4)
	s_waitcnt lgkmcnt(0)
	s_barrier
	v_mfma_f32_16x16x32_bf16 v[60:63], v[128:131], v[144:147], v[60:63]
	v_mfma_f32_16x16x32_bf16 v[56:59], v[136:139], v[144:147], v[56:59]
	v_mfma_f32_16x16x32_bf16 v[52:55], v[128:131], v[152:155], v[52:55]
	v_mfma_f32_16x16x32_bf16 v[48:51], v[136:139], v[152:155], v[48:51]
	v_mfma_f32_16x16x32_bf16 v[44:47], v[128:131], v[160:163], v[44:47]
	v_mfma_f32_16x16x32_bf16 v[40:43], v[136:139], v[160:163], v[40:43]
	v_mfma_f32_16x16x32_bf16 v[36:39], v[128:131], v[168:171], v[36:39]
	v_mfma_f32_16x16x32_bf16 v[32:35], v[136:139], v[168:171], v[32:35]
	v_mfma_f32_16x16x32_bf16 v[60:63], v[132:135], v[148:151], v[60:63]
	v_mfma_f32_16x16x32_bf16 v[56:59], v[140:143], v[148:151], v[56:59]
	v_mfma_f32_16x16x32_bf16 v[52:55], v[132:135], v[156:159], v[52:55]
	v_mfma_f32_16x16x32_bf16 v[48:51], v[140:143], v[156:159], v[48:51]
	v_mfma_f32_16x16x32_bf16 v[44:47], v[132:135], v[164:167], v[44:47]
	v_mfma_f32_16x16x32_bf16 v[40:43], v[140:143], v[164:167], v[40:43]
	v_mfma_f32_16x16x32_bf16 v[36:39], v[132:135], v[172:175], v[36:39]
	v_mfma_f32_16x16x32_bf16 v[32:35], v[140:143], v[172:175], v[32:35]
	v_mfma_f32_16x16x32_bf16 v[28:31], v[176:179], v[144:147], v[28:31]
	v_mfma_f32_16x16x32_bf16 v[24:27], v[184:187], v[144:147], v[24:27]
	v_mfma_f32_16x16x32_bf16 v[20:23], v[176:179], v[152:155], v[20:23]
	v_mfma_f32_16x16x32_bf16 v[16:19], v[184:187], v[152:155], v[16:19]
	v_mfma_f32_16x16x32_bf16 v[12:15], v[176:179], v[160:163], v[12:15]
	v_mfma_f32_16x16x32_bf16 v[8:11], v[184:187], v[160:163], v[8:11]
	v_mfma_f32_16x16x32_bf16 v[4:7], v[176:179], v[168:171], v[4:7]
	v_mfma_f32_16x16x32_bf16 v[0:3], v[184:187], v[168:171], v[0:3]
	v_mfma_f32_16x16x32_bf16 v[28:31], v[180:183], v[148:151], v[28:31]
	v_mfma_f32_16x16x32_bf16 v[24:27], v[188:191], v[148:151], v[24:27]
	v_mfma_f32_16x16x32_bf16 v[20:23], v[180:183], v[156:159], v[20:23]
	v_mfma_f32_16x16x32_bf16 v[16:19], v[188:191], v[156:159], v[16:19]
	v_mfma_f32_16x16x32_bf16 v[12:15], v[180:183], v[164:167], v[12:15]
	v_mfma_f32_16x16x32_bf16 v[8:11], v[188:191], v[164:167], v[8:11]
	v_mfma_f32_16x16x32_bf16 v[4:7], v[180:183], v[172:175], v[4:7]
	v_mfma_f32_16x16x32_bf16 v[0:3], v[188:191], v[172:175], v[0:3]
	s_add_i32 s55, s55, 2
	s_add_u32 s44, s44, 0x100
	s_addc_u32 s45, s45, 0
	s_add_u32 s41, s41, 0x100
	s_addc_u32 s43, s43, 0
	s_cmp_gt_u32 s55, 13
	s_barrier
	s_cbranch_scc0 .LBB0_400
	s_cmp_lt_i32 s14, 2
	v_lshl_add_u32 v208, s15, 8, v244
	v_lshl_or_b32 v206, s54, 8, v246
	s_cselect_b64 s[8:9], -1, 0
	s_cmp_gt_i32 s14, 1
	v_mov_b64_e32 v[128:129], s[26:27]
	s_cselect_b64 s[92:93], -1, 0
	s_cmp_lg_u64 s[8:9], 0
	v_ashrrev_i32_e32 v207, 31, v206
	v_mad_i64_i32 v[128:129], s[6:7], v208, s58, v[128:129]
	s_addc_u32 s15, s14, 0
	s_lshl_b32 s46, s14, 11
	v_lshl_add_u64 v[128:129], v[206:207], 1, v[128:129]
	s_ashr_i32 s47, s46, 31
	v_lshl_add_u64 v[128:129], v[128:129], 0, s[34:35]
	v_lshl_add_u64 v[130:131], s[46:47], 1, v[128:129]
	global_load_dwordx4 v[188:191], v[130:131], off
	s_lshl_b32 s52, s15, 11
	s_ashr_i32 s53, s52, 31
	v_mov_b32_e32 v148, 0
	s_and_b64 vcc, exec, s[92:93]
	v_lshl_add_u64 v[128:129], s[52:53], 1, v[128:129]
	v_mov_b32_e32 v180, 0
	v_mov_b32_e32 v181, 0
	v_mov_b32_e32 v182, 0
	v_mov_b32_e32 v183, 0
	s_cbranch_vccnz .LBB0_403
	global_load_dwordx4 v[180:183], v[128:129], off

; #define PG8_STAGE(bufoff, gbase, voff) do { _Pragma("unroll") for (int _i = 0; _i < 2; ++_i) \
;         __builtin_amdgcn_global_load_lds((const unsigned*)((const char*)(gbase) + (voff)[_i]), (LAS unsigned*)(lds + (bufoff) + ldsw + _i * 8192), 16, 0, 0); } while (0)
; #define PG8_LDA(dst, b, h) do { _Pragma("unroll") for (int m = 0; m < 4; ++m) _Pragma("unroll") for (int k = 0; k < 2; ++k) dst[m][k] = *(const LAS bf16x8*)(lds + PG8_SA(b, h) + aoff + m * 2048 + k * 1024); } while (0)
; #define PG8_LDB(dst, b, h) do { _Pragma("unroll") for (int n = 0; n < 2; ++n) _Pragma("unroll") for (int k = 0; k < 2; ++k) dst[n][k] = *(const LAS bf16x8*)(lds + PG8_SB(b, h) + boff + n * 2048 + k * 1024); } while (0)
; #define PG8_MMA(ai, bj, At, Bt) do { __builtin_amdgcn_s_setprio(1); _Pragma("unroll") for (int m = 0; m < 4; ++m) _Pragma("unroll") for (int n = 0; n < 2; ++n) _Pragma("unroll") for (int k = 0; k < 2; ++k) \
;         acc[ai][bj][m][n] = __builtin_amdgcn_mfma_f32_16x16x32_bf16(Bt[n][k], At[m][k], acc[ai][bj][m][n], 0, 0, 0); __builtin_amdgcn_s_setprio(0); } while (0)
; #define PG8_WAIT_V(n) asm volatile("s_waitcnt vmcnt(" #n ")" ::: "memory")
; #define PG8_WAIT_L(n) asm volatile("s_waitcnt lgkmcnt(" #n ")" ::: "memory")
; #define PG8_BAR __builtin_amdgcn_s_barrier()
; #define PG8_SCHED __builtin_amdgcn_sched_barrier(0)
; template <class Prog>
; __device__ __forceinline__ void gemm_phase(LAS unsigned char* lds, const int K, const Prog& S) {
;     ...
;             PG8_LDB(B0, 0, 0); PG8_SCHED; PG8_LDA(At, 0, 0); PG8_STAGE(PG8_SA(1, 1), a1 + hstep, voffA);
;             PG8_WAIT_L(8); PG8_BAR; PG8_WAIT_L(0); PG8_MMA(0, 0, At, B0); PG8_BAR; PG8_SCHED;
;             PG8_LDB(B1, 0, 1); PG8_STAGE(PG8_SB(0, 0), b2, voffB);
;             PG8_BAR; PG8_WAIT_L(0); PG8_MMA(0, 1, At, B1); PG8_BAR;
;             PG8_LDA(At, 0, 1); PG8_STAGE(PG8_SA(0, 0), a2, voffA);
;             PG8_BAR; PG8_WAIT_L(0); PG8_MMA(1, 0, At, B0); PG8_BAR; PG8_SCHED;
;             PG8_STAGE(PG8_SB(0, 1), b2 + hstep, voffB);
;             PG8_WAIT_V(6); PG8_BAR; PG8_MMA(1, 1, At, B1); PG8_BAR;
.LBB0_570:
	s_add_u32 s46, s46, 0x80080
	s_addc_u32 s47, s47, 0
	s_add_u32 s41, s52, 0x100
	s_addc_u32 s43, s53, 0
	s_mov_b32 s54, -2
	s_waitcnt lgkmcnt(0)
	s_waitcnt vmcnt(16)
	v_add_u32_e32 v202, 0x10000, v215
	s_add_u32 s52, s46, 0xfff80080
	s_addc_u32 s53, s47, -1
	s_cmp_eq_u32 s54, 28
	s_cselect_b32 s93, s7, s53
	s_cselect_b32 s92, s6, s52
	s_cselect_b32 s53, s45, s43
	s_cselect_b32 s52, s44, s41
	s_add_u32 vcc_lo, s46, 0xfff80000
	s_addc_u32 vcc_hi, s47, -1
	ds_read_b128 v[128:131], v202
	ds_read_b128 v[132:135], v202 offset:1024
	ds_read_b128 v[136:139], v202 offset:2048
	ds_read_b128 v[140:143], v202 offset:3072
	s_add_i32 m0, s75, 0x8000
	ds_read_b128 v[176:179], v202 offset:16384
	ds_read_b128 v[180:183], v202 offset:17408
	ds_read_b128 v[184:187], v202 offset:18432
	ds_read_b128 v[198:201], v202 offset:19456
	global_load_lds_dwordx4 v190, vcc
	s_add_i32 m0, s75, 0xa000
	ds_read_b128 v[144:147], v217
	ds_read_b128 v[148:151], v217 offset:1024
	ds_read_b128 v[152:155], v217 offset:2048
	ds_read_b128 v[156:159], v217 offset:3072
	global_load_lds_dwordx4 v196, vcc
	s_add_i32 m0, s75, 0xc000
	ds_read_b128 v[160:163], v217 offset:4096
	ds_read_b128 v[164:167], v217 offset:5120
	ds_read_b128 v[168:171], v217 offset:6144
	ds_read_b128 v[172:175], v217 offset:7168
	global_load_lds_dwordx4 v190, s[46:47]
	s_add_i32 m0, s75, 0xe000
	s_nop 0
	global_load_lds_dwordx4 v196, s[46:47]
	s_waitcnt lgkmcnt(0)
	s_barrier
	v_mfma_f32_16x16x32_bf16 v[124:127], v[128:131], v[144:147], 0
	v_mfma_f32_16x16x32_bf16 v[120:123], v[136:139], v[144:147], 0
	v_mfma_f32_16x16x32_bf16 v[108:111], v[128:131], v[152:155], 0
	v_mfma_f32_16x16x32_bf16 v[104:107], v[136:139], v[152:155], 0
	v_mfma_f32_16x16x32_bf16 v[92:95], v[128:131], v[160:163], 0
	v_mfma_f32_16x16x32_bf16 v[88:91], v[136:139], v[160:163], 0
	v_mfma_f32_16x16x32_bf16 v[76:79], v[128:131], v[168:171], 0
	v_mfma_f32_16x16x32_bf16 v[72:75], v[136:139], v[168:171], 0
	v_mfma_f32_16x16x32_bf16 v[124:127], v[132:135], v[148:151], v[124:127]
	v_mfma_f32_16x16x32_bf16 v[120:123], v[140:143], v[148:151], v[120:123]
	v_mfma_f32_16x16x32_bf16 v[108:111], v[132:135], v[156:159], v[108:111]
	v_mfma_f32_16x16x32_bf16 v[104:107], v[140:143], v[156:159], v[104:107]
	v_mfma_f32_16x16x32_bf16 v[92:95], v[132:135], v[164:167], v[92:95]
	v_mfma_f32_16x16x32_bf16 v[88:91], v[140:143], v[164:167], v[88:91]
	v_mfma_f32_16x16x32_bf16 v[76:79], v[132:135], v[172:175], v[76:79]
	v_mfma_f32_16x16x32_bf16 v[72:75], v[140:143], v[172:175], v[72:75]
	v_mfma_f32_16x16x32_bf16 v[116:119], v[176:179], v[144:147], 0
	v_mfma_f32_16x16x32_bf16 v[112:115], v[184:187], v[144:147], 0
	v_mfma_f32_16x16x32_bf16 v[100:103], v[176:179], v[152:155], 0
	v_mfma_f32_16x16x32_bf16 v[96:99], v[184:187], v[152:155], 0
	v_mfma_f32_16x16x32_bf16 v[84:87], v[176:179], v[160:163], 0
	v_mfma_f32_16x16x32_bf16 v[80:83], v[184:187], v[160:163], 0
	v_mfma_f32_16x16x32_bf16 v[68:71], v[176:179], v[168:171], 0
	v_mfma_f32_16x16x32_bf16 v[64:67], v[184:187], v[168:171], 0
	v_mfma_f32_16x16x32_bf16 v[116:119], v[180:183], v[148:151], v[116:119]
	v_mfma_f32_16x16x32_bf16 v[112:115], v[198:201], v[148:151], v[112:115]
	v_mfma_f32_16x16x32_bf16 v[100:103], v[180:183], v[156:159], v[100:103]
	v_mfma_f32_16x16x32_bf16 v[96:99], v[198:201], v[156:159], v[96:99]
	v_mfma_f32_16x16x32_bf16 v[84:87], v[180:183], v[164:167], v[84:87]
	v_mfma_f32_16x16x32_bf16 v[80:83], v[198:201], v[164:167], v[80:83]
	v_mfma_f32_16x16x32_bf16 v[68:71], v[180:183], v[172:175], v[68:71]
	v_mfma_f32_16x16x32_bf16 v[64:67], v[198:201], v[172:175], v[64:67]
	s_barrier
	ds_read_b128 v[144:147], v217 offset:16384
	ds_read_b128 v[148:151], v217 offset:17408
	ds_read_b128 v[152:155], v217 offset:18432
	ds_read_b128 v[156:159], v217 offset:19456
	s_add_i32 m0, s75, 0x10000
	ds_read_b128 v[160:163], v217 offset:20480
	ds_read_b128 v[164:167], v217 offset:21504
	ds_read_b128 v[168:171], v217 offset:22528
	ds_read_b128 v[172:175], v217 offset:23552
	global_load_lds_dwordx4 v192, s[52:53]
	s_add_i32 m0, s75, 0x12000
	s_nop 0
	global_load_lds_dwordx4 v188, s[52:53]
	s_add_u32 vcc_lo, s52, 0x80000
	s_addc_u32 vcc_hi, s53, 0
	s_add_i32 m0, s75, 0x14000
	s_nop 0
	global_load_lds_dwordx4 v192, vcc
	s_add_i32 m0, s75, 0x16000
	s_nop 0
	global_load_lds_dwordx4 v188, vcc
	s_waitcnt vmcnt(4)
	s_waitcnt lgkmcnt(0)
	s_barrier
	v_mfma_f32_16x16x32_bf16 v[60:63], v[128:131], v[144:147], 0
	v_mfma_f32_16x16x32_bf16 v[56:59], v[136:139], v[144:147], 0
	v_mfma_f32_16x16x32_bf16 v[44:47], v[128:131], v[152:155], 0
	v_mfma_f32_16x16x32_bf16 v[40:43], v[136:139], v[152:155], 0
	v_mfma_f32_16x16x32_bf16 v[28:31], v[128:131], v[160:163], 0
	v_mfma_f32_16x16x32_bf16 v[24:27], v[136:139], v[160:163], 0
	v_mfma_f32_16x16x32_bf16 v[12:15], v[128:131], v[168:171], 0
	v_mfma_f32_16x16x32_bf16 v[8:11], v[136:139], v[168:171], 0
	v_mfma_f32_16x16x32_bf16 v[60:63], v[132:135], v[148:151], v[60:63]
	v_mfma_f32_16x16x32_bf16 v[56:59], v[140:143], v[148:151], v[56:59]
	v_mfma_f32_16x16x32_bf16 v[44:47], v[132:135], v[156:159], v[44:47]
	v_mfma_f32_16x16x32_bf16 v[40:43], v[140:143], v[156:159], v[40:43]
	v_mfma_f32_16x16x32_bf16 v[28:31], v[132:135], v[164:167], v[28:31]
	v_mfma_f32_16x16x32_bf16 v[24:27], v[140:143], v[164:167], v[24:27]
	v_mfma_f32_16x16x32_bf16 v[12:15], v[132:135], v[172:175], v[12:15]
	v_mfma_f32_16x16x32_bf16 v[8:11], v[140:143], v[172:175], v[8:11]
	v_mfma_f32_16x16x32_bf16 v[52:55], v[176:179], v[144:147], 0
	v_mfma_f32_16x16x32_bf16 v[48:51], v[184:187], v[144:147], 0
	v_mfma_f32_16x16x32_bf16 v[36:39], v[176:179], v[152:155], 0
	v_mfma_f32_16x16x32_bf16 v[32:35], v[184:187], v[152:155], 0
	v_mfma_f32_16x16x32_bf16 v[20:23], v[176:179], v[160:163], 0
	v_mfma_f32_16x16x32_bf16 v[16:19], v[184:187], v[160:163], 0
	v_mfma_f32_16x16x32_bf16 v[4:7], v[176:179], v[168:171], 0
	v_mfma_f32_16x16x32_bf16 v[0:3], v[184:187], v[168:171], 0
	v_mfma_f32_16x16x32_bf16 v[52:55], v[180:183], v[148:151], v[52:55]
	v_mfma_f32_16x16x32_bf16 v[48:51], v[198:201], v[148:151], v[48:51]
	v_mfma_f32_16x16x32_bf16 v[36:39], v[180:183], v[156:159], v[36:39]
	v_mfma_f32_16x16x32_bf16 v[32:35], v[198:201], v[156:159], v[32:35]
	v_mfma_f32_16x16x32_bf16 v[20:23], v[180:183], v[164:167], v[20:23]
	v_mfma_f32_16x16x32_bf16 v[16:19], v[198:201], v[164:167], v[16:19]
	v_mfma_f32_16x16x32_bf16 v[4:7], v[180:183], v[172:175], v[4:7]
	v_mfma_f32_16x16x32_bf16 v[0:3], v[198:201], v[172:175], v[0:3]
	s_barrier
; #define PG8_STAGE(bufoff, gbase, voff) do { _Pragma("unroll") for (int _i = 0; _i < 2; ++_i) \
;         __builtin_amdgcn_global_load_lds((const unsigned*)((const char*)(gbase) + (voff)[_i]), (LAS unsigned*)(lds + (bufoff) + ldsw + _i * 8192), 16, 0, 0); } while (0)
; #define PG8_LDA(dst, b, h) do { _Pragma("unroll") for (int m = 0; m < 4; ++m) _Pragma("unroll") for (int k = 0; k < 2; ++k) dst[m][k] = *(const LAS bf16x8*)(lds + PG8_SA(b, h) + aoff + m * 2048 + k * 1024); } while (0)
; #define PG8_LDB(dst, b, h) do { _Pragma("unroll") for (int n = 0; n < 2; ++n) _Pragma("unroll") for (int k = 0; k < 2; ++k) dst[n][k] = *(const LAS bf16x8*)(lds + PG8_SB(b, h) + boff + n * 2048 + k * 1024); } while (0)
; #define PG8_MMA(ai, bj, At, Bt) do { __builtin_amdgcn_s_setprio(1); _Pragma("unroll") for (int m = 0; m < 4; ++m) _Pragma("unroll") for (int n = 0; n < 2; ++n) _Pragma("unroll") for (int k = 0; k < 2; ++k) \
;         acc[ai][bj][m][n] = __builtin_amdgcn_mfma_f32_16x16x32_bf16(Bt[n][k], At[m][k], acc[ai][bj][m][n], 0, 0, 0); __builtin_amdgcn_s_setprio(0); } while (0)
; #define PG8_WAIT_V(n) asm volatile("s_waitcnt vmcnt(" #n ")" ::: "memory")
; #define PG8_WAIT_L(n) asm volatile("s_waitcnt lgkmcnt(" #n ")" ::: "memory")
; #define PG8_BAR __builtin_amdgcn_s_barrier()
; #define PG8_SCHED __builtin_amdgcn_sched_barrier(0)
; template <class Prog>
; __device__ __forceinline__ void gemm_phase(LAS unsigned char* lds, const int K, const Prog& S) {
;     ...
;             PG8_LDB(B0, 1, 0); PG8_SCHED; PG8_LDA(At, 1, 0); PG8_STAGE(PG8_SA(0, 1), a2 + hstep, voffA);
;             PG8_WAIT_L(8); PG8_BAR; PG8_WAIT_L(0); PG8_MMA(0, 0, At, B0); PG8_BAR; PG8_SCHED;
;             PG8_LDB(B1, 1, 1); PG8_STAGE(PG8_SB(1, 0), b3, voffB);
;             PG8_BAR; PG8_WAIT_L(0); PG8_MMA(0, 1, At, B1); PG8_BAR;
;             PG8_LDA(At, 1, 1); PG8_STAGE(PG8_SA(1, 0), a3, voffA);
;             PG8_BAR; PG8_WAIT_L(0); PG8_MMA(1, 0, At, B0); PG8_BAR; PG8_SCHED;
;             PG8_STAGE(PG8_SB(1, 1), b3 + hstep, voffB);
;             PG8_WAIT_V(6); PG8_BAR; PG8_MMA(1, 1, At, B1); PG8_BAR;
	s_add_u32 vcc_lo, s92, 0x80000
	s_addc_u32 vcc_hi, s93, 0
	ds_read_b128 v[128:131], v202 offset:32768
	ds_read_b128 v[132:135], v202 offset:33792
	ds_read_b128 v[136:139], v202 offset:34816
	ds_read_b128 v[140:143], v202 offset:35840
	s_mov_b32 m0, s75
	ds_read_b128 v[176:179], v202 offset:49152
	ds_read_b128 v[180:183], v202 offset:50176
	ds_read_b128 v[184:187], v202 offset:51200
	ds_read_b128 v[198:201], v202 offset:52224
	global_load_lds_dwordx4 v192, s[92:93]
	s_add_i32 m0, s75, 0x2000
	ds_read_b128 v[144:147], v217 offset:32768
	ds_read_b128 v[148:151], v217 offset:33792
	ds_read_b128 v[152:155], v217 offset:34816
	ds_read_b128 v[156:159], v217 offset:35840
	global_load_lds_dwordx4 v188, s[92:93]
	s_add_i32 m0, s75, 0x4000
	ds_read_b128 v[160:163], v217 offset:36864
	ds_read_b128 v[164:167], v217 offset:37888
	ds_read_b128 v[168:171], v217 offset:38912
	ds_read_b128 v[172:175], v217 offset:39936
	global_load_lds_dwordx4 v192, vcc
	s_add_i32 m0, s75, 0x6000
	s_nop 0
	global_load_lds_dwordx4 v188, vcc
	s_waitcnt lgkmcnt(0)
	s_barrier
	v_mfma_f32_16x16x32_bf16 v[124:127], v[128:131], v[144:147], v[124:127]
	v_mfma_f32_16x16x32_bf16 v[120:123], v[136:139], v[144:147], v[120:123]
	v_mfma_f32_16x16x32_bf16 v[108:111], v[128:131], v[152:155], v[108:111]
	v_mfma_f32_16x16x32_bf16 v[104:107], v[136:139], v[152:155], v[104:107]
	v_mfma_f32_16x16x32_bf16 v[92:95], v[128:131], v[160:163], v[92:95]
	v_mfma_f32_16x16x32_bf16 v[88:91], v[136:139], v[160:163], v[88:91]
	v_mfma_f32_16x16x32_bf16 v[76:79], v[128:131], v[168:171], v[76:79]
	v_mfma_f32_16x16x32_bf16 v[72:75], v[136:139], v[168:171], v[72:75]
	v_mfma_f32_16x16x32_bf16 v[124:127], v[132:135], v[148:151], v[124:127]
	v_mfma_f32_16x16x32_bf16 v[120:123], v[140:143], v[148:151], v[120:123]
	v_mfma_f32_16x16x32_bf16 v[108:111], v[132:135], v[156:159], v[108:111]
	v_mfma_f32_16x16x32_bf16 v[104:107], v[140:143], v[156:159], v[104:107]
	v_mfma_f32_16x16x32_bf16 v[92:95], v[132:135], v[164:167], v[92:95]
	v_mfma_f32_16x16x32_bf16 v[88:91], v[140:143], v[164:167], v[88:91]
	v_mfma_f32_16x16x32_bf16 v[76:79], v[132:135], v[172:175], v[76:79]
	v_mfma_f32_16x16x32_bf16 v[72:75], v[140:143], v[172:175], v[72:75]
	v_mfma_f32_16x16x32_bf16 v[116:119], v[176:179], v[144:147], v[116:119]
	v_mfma_f32_16x16x32_bf16 v[112:115], v[184:187], v[144:147], v[112:115]
	v_mfma_f32_16x16x32_bf16 v[100:103], v[176:179], v[152:155], v[100:103]
	v_mfma_f32_16x16x32_bf16 v[96:99], v[184:187], v[152:155], v[96:99]
	v_mfma_f32_16x16x32_bf16 v[84:87], v[176:179], v[160:163], v[84:87]
	v_mfma_f32_16x16x32_bf16 v[80:83], v[184:187], v[160:163], v[80:83]
	v_mfma_f32_16x16x32_bf16 v[68:71], v[176:179], v[168:171], v[68:71]
	v_mfma_f32_16x16x32_bf16 v[64:67], v[184:187], v[168:171], v[64:67]
	v_mfma_f32_16x16x32_bf16 v[116:119], v[180:183], v[148:151], v[116:119]
	v_mfma_f32_16x16x32_bf16 v[112:115], v[198:201], v[148:151], v[112:115]
	v_mfma_f32_16x16x32_bf16 v[100:103], v[180:183], v[156:159], v[100:103]
	v_mfma_f32_16x16x32_bf16 v[96:99], v[198:201], v[156:159], v[96:99]
	v_mfma_f32_16x16x32_bf16 v[84:87], v[180:183], v[164:167], v[84:87]
	v_mfma_f32_16x16x32_bf16 v[80:83], v[198:201], v[164:167], v[80:83]
	v_mfma_f32_16x16x32_bf16 v[68:71], v[180:183], v[172:175], v[68:71]
	v_mfma_f32_16x16x32_bf16 v[64:67], v[198:201], v[172:175], v[64:67]
	s_nop 0
	s_barrier
	s_add_u32 vcc_lo, s52, 0x80
	s_addc_u32 vcc_hi, s53, 0
	ds_read_b128 v[144:147], v217 offset:49152
	ds_read_b128 v[148:151], v217 offset:50176
	ds_read_b128 v[152:155], v217 offset:51200
	ds_read_b128 v[156:159], v217 offset:52224
	s_add_i32 m0, s75, 0x18000
	ds_read_b128 v[160:163], v217 offset:53248
	ds_read_b128 v[164:167], v217 offset:54272
	ds_read_b128 v[168:171], v217 offset:55296
	ds_read_b128 v[172:175], v217 offset:56320
	global_load_lds_dwordx4 v192, vcc
	s_add_i32 m0, s75, 0x1a000
	s_nop 0
	global_load_lds_dwordx4 v188, vcc
	s_add_u32 vcc_lo, s52, 0x80080
	s_addc_u32 vcc_hi, s53, 0
	s_add_i32 m0, s75, 0x1c000
	s_nop 0
	global_load_lds_dwordx4 v192, vcc
	s_add_i32 m0, s75, 0x1e000
	s_nop 0
	global_load_lds_dwordx4 v188, vcc
	s_waitcnt vmcnt(4)
	s_waitcnt lgkmcnt(0)
	s_barrier
	v_mfma_f32_16x16x32_bf16 v[60:63], v[128:131], v[144:147], v[60:63]
	v_mfma_f32_16x16x32_bf16 v[56:59], v[136:139], v[144:147], v[56:59]
	v_mfma_f32_16x16x32_bf16 v[44:47], v[128:131], v[152:155], v[44:47]
	v_mfma_f32_16x16x32_bf16 v[40:43], v[136:139], v[152:155], v[40:43]
	v_mfma_f32_16x16x32_bf16 v[28:31], v[128:131], v[160:163], v[28:31]
	v_mfma_f32_16x16x32_bf16 v[24:27], v[136:139], v[160:163], v[24:27]
	v_mfma_f32_16x16x32_bf16 v[12:15], v[128:131], v[168:171], v[12:15]
	v_mfma_f32_16x16x32_bf16 v[8:11], v[136:139], v[168:171], v[8:11]
	v_mfma_f32_16x16x32_bf16 v[60:63], v[132:135], v[148:151], v[60:63]
	v_mfma_f32_16x16x32_bf16 v[56:59], v[140:143], v[148:151], v[56:59]
	v_mfma_f32_16x16x32_bf16 v[44:47], v[132:135], v[156:159], v[44:47]
	v_mfma_f32_16x16x32_bf16 v[40:43], v[140:143], v[156:159], v[40:43]
	v_mfma_f32_16x16x32_bf16 v[28:31], v[132:135], v[164:167], v[28:31]
	v_mfma_f32_16x16x32_bf16 v[24:27], v[140:143], v[164:167], v[24:27]
	v_mfma_f32_16x16x32_bf16 v[12:15], v[132:135], v[172:175], v[12:15]
	v_mfma_f32_16x16x32_bf16 v[8:11], v[140:143], v[172:175], v[8:11]
	v_mfma_f32_16x16x32_bf16 v[52:55], v[176:179], v[144:147], v[52:55]
	v_mfma_f32_16x16x32_bf16 v[48:51], v[184:187], v[144:147], v[48:51]
	v_mfma_f32_16x16x32_bf16 v[36:39], v[176:179], v[152:155], v[36:39]
	v_mfma_f32_16x16x32_bf16 v[32:35], v[184:187], v[152:155], v[32:35]
	v_mfma_f32_16x16x32_bf16 v[20:23], v[176:179], v[160:163], v[20:23]
	v_mfma_f32_16x16x32_bf16 v[16:19], v[184:187], v[160:163], v[16:19]
	v_mfma_f32_16x16x32_bf16 v[4:7], v[176:179], v[168:171], v[4:7]
	v_mfma_f32_16x16x32_bf16 v[0:3], v[184:187], v[168:171], v[0:3]
	v_mfma_f32_16x16x32_bf16 v[52:55], v[180:183], v[148:151], v[52:55]
	v_mfma_f32_16x16x32_bf16 v[48:51], v[198:201], v[148:151], v[48:51]
	v_mfma_f32_16x16x32_bf16 v[36:39], v[180:183], v[156:159], v[36:39]
	v_mfma_f32_16x16x32_bf16 v[32:35], v[198:201], v[156:159], v[32:35]
	v_mfma_f32_16x16x32_bf16 v[20:23], v[180:183], v[164:167], v[20:23]
	v_mfma_f32_16x16x32_bf16 v[16:19], v[198:201], v[164:167], v[16:19]
	v_mfma_f32_16x16x32_bf16 v[4:7], v[180:183], v[172:175], v[4:7]
	v_mfma_f32_16x16x32_bf16 v[0:3], v[198:201], v[172:175], v[0:3]
	s_add_i32 s54, s54, 2
	s_add_u32 s46, s46, 0x100
	s_addc_u32 s47, s47, 0
	s_add_u32 s41, s41, 0x100
	s_addc_u32 s43, s43, 0
	s_cmp_gt_u32 s54, 29
	s_barrier
	.p2align 6
; #define PG8_STAGE(bufoff, gbase, voff) do { _Pragma("unroll") for (int _i = 0; _i < 2; ++_i) \
;         __builtin_amdgcn_global_load_lds((const unsigned*)((const char*)(gbase) + (voff)[_i]), (LAS unsigned*)(lds + (bufoff) + ldsw + _i * 8192), 16, 0, 0); } while (0)
; #define PG8_LDA(dst, b, h) do { _Pragma("unroll") for (int m = 0; m < 4; ++m) _Pragma("unroll") for (int k = 0; k < 2; ++k) dst[m][k] = *(const LAS bf16x8*)(lds + PG8_SA(b, h) + aoff + m * 2048 + k * 1024); } while (0)
; #define PG8_LDB(dst, b, h) do { _Pragma("unroll") for (int n = 0; n < 2; ++n) _Pragma("unroll") for (int k = 0; k < 2; ++k) dst[n][k] = *(const LAS bf16x8*)(lds + PG8_SB(b, h) + boff + n * 2048 + k * 1024); } while (0)
; #define PG8_MMA(ai, bj, At, Bt) do { __builtin_amdgcn_s_setprio(1); _Pragma("unroll") for (int m = 0; m < 4; ++m) _Pragma("unroll") for (int n = 0; n < 2; ++n) _Pragma("unroll") for (int k = 0; k < 2; ++k) \
;         acc[ai][bj][m][n] = __builtin_amdgcn_mfma_f32_16x16x32_bf16(Bt[n][k], At[m][k], acc[ai][bj][m][n], 0, 0, 0); __builtin_amdgcn_s_setprio(0); } while (0)
; #define PG8_WAIT_V(n) asm volatile("s_waitcnt vmcnt(" #n ")" ::: "memory")
; #define PG8_WAIT_L(n) asm volatile("s_waitcnt lgkmcnt(" #n ")" ::: "memory")
; #define PG8_BAR __builtin_amdgcn_s_barrier()
; #define PG8_SCHED __builtin_amdgcn_sched_barrier(0)
; template <class Prog>
; __device__ __forceinline__ void gemm_phase(LAS unsigned char* lds, const int K, const Prog& S) {
;     ...
;             PG8_LDB(B0, 0, 0); PG8_SCHED; PG8_LDA(At, 0, 0); PG8_STAGE(PG8_SA(1, 1), a1 + hstep, voffA);
;             PG8_WAIT_L(8); PG8_BAR; PG8_WAIT_L(0); PG8_MMA(0, 0, At, B0); PG8_BAR; PG8_SCHED;
;             PG8_LDB(B1, 0, 1); PG8_STAGE(PG8_SB(0, 0), b2, voffB);
;             PG8_BAR; PG8_WAIT_L(0); PG8_MMA(0, 1, At, B1); PG8_BAR;
;             PG8_LDA(At, 0, 1); PG8_STAGE(PG8_SA(0, 0), a2, voffA);
;             PG8_BAR; PG8_WAIT_L(0); PG8_MMA(1, 0, At, B0); PG8_BAR; PG8_SCHED;
;             PG8_STAGE(PG8_SB(0, 1), b2 + hstep, voffB);
;             PG8_WAIT_V(6); PG8_BAR; PG8_MMA(1, 1, At, B1); PG8_BAR;
.LBB0_571:
	s_add_u32 s52, s46, 0xfff80080
	s_addc_u32 s53, s47, -1
	s_cmp_eq_u32 s54, 28
	s_cselect_b32 s93, s7, s53
	s_cselect_b32 s92, s6, s52
	s_cselect_b32 s53, s45, s43
	s_cselect_b32 s52, s44, s41
	s_add_u32 vcc_lo, s46, 0xfff80000
	s_addc_u32 vcc_hi, s47, -1
	ds_read_b128 v[128:131], v202
	ds_read_b128 v[132:135], v202 offset:1024
	ds_read_b128 v[136:139], v202 offset:2048
	ds_read_b128 v[140:143], v202 offset:3072
	s_add_i32 m0, s75, 0x8000
	ds_read_b128 v[176:179], v202 offset:16384
	ds_read_b128 v[180:183], v202 offset:17408
	ds_read_b128 v[184:187], v202 offset:18432
	ds_read_b128 v[198:201], v202 offset:19456
	global_load_lds_dwordx4 v190, vcc
	s_add_i32 m0, s75, 0xa000
	ds_read_b128 v[144:147], v217
	ds_read_b128 v[148:151], v217 offset:1024
	ds_read_b128 v[152:155], v217 offset:2048
	ds_read_b128 v[156:159], v217 offset:3072
	global_load_lds_dwordx4 v196, vcc
	s_add_i32 m0, s75, 0xc000
	ds_read_b128 v[160:163], v217 offset:4096
	ds_read_b128 v[164:167], v217 offset:5120
	ds_read_b128 v[168:171], v217 offset:6144
	ds_read_b128 v[172:175], v217 offset:7168
	global_load_lds_dwordx4 v190, s[46:47]
	s_add_i32 m0, s75, 0xe000
	s_nop 0
	global_load_lds_dwordx4 v196, s[46:47]
	s_waitcnt lgkmcnt(0)
	s_barrier
	v_mfma_f32_16x16x32_bf16 v[124:127], v[128:131], v[144:147], v[124:127]
	v_mfma_f32_16x16x32_bf16 v[120:123], v[136:139], v[144:147], v[120:123]
	v_mfma_f32_16x16x32_bf16 v[108:111], v[128:131], v[152:155], v[108:111]
	v_mfma_f32_16x16x32_bf16 v[104:107], v[136:139], v[152:155], v[104:107]
	v_mfma_f32_16x16x32_bf16 v[92:95], v[128:131], v[160:163], v[92:95]
	v_mfma_f32_16x16x32_bf16 v[88:91], v[136:139], v[160:163], v[88:91]
	v_mfma_f32_16x16x32_bf16 v[76:79], v[128:131], v[168:171], v[76:79]
	v_mfma_f32_16x16x32_bf16 v[72:75], v[136:139], v[168:171], v[72:75]
	v_mfma_f32_16x16x32_bf16 v[124:127], v[132:135], v[148:151], v[124:127]
	v_mfma_f32_16x16x32_bf16 v[120:123], v[140:143], v[148:151], v[120:123]
	v_mfma_f32_16x16x32_bf16 v[108:111], v[132:135], v[156:159], v[108:111]
	v_mfma_f32_16x16x32_bf16 v[104:107], v[140:143], v[156:159], v[104:107]
	v_mfma_f32_16x16x32_bf16 v[92:95], v[132:135], v[164:167], v[92:95]
	v_mfma_f32_16x16x32_bf16 v[88:91], v[140:143], v[164:167], v[88:91]
	v_mfma_f32_16x16x32_bf16 v[76:79], v[132:135], v[172:175], v[76:79]
	v_mfma_f32_16x16x32_bf16 v[72:75], v[140:143], v[172:175], v[72:75]
	v_mfma_f32_16x16x32_bf16 v[116:119], v[176:179], v[144:147], v[116:119]
	v_mfma_f32_16x16x32_bf16 v[112:115], v[184:187], v[144:147], v[112:115]
	v_mfma_f32_16x16x32_bf16 v[100:103], v[176:179], v[152:155], v[100:103]
	v_mfma_f32_16x16x32_bf16 v[96:99], v[184:187], v[152:155], v[96:99]
	v_mfma_f32_16x16x32_bf16 v[84:87], v[176:179], v[160:163], v[84:87]
	v_mfma_f32_16x16x32_bf16 v[80:83], v[184:187], v[160:163], v[80:83]
	v_mfma_f32_16x16x32_bf16 v[68:71], v[176:179], v[168:171], v[68:71]
	v_mfma_f32_16x16x32_bf16 v[64:67], v[184:187], v[168:171], v[64:67]
	v_mfma_f32_16x16x32_bf16 v[116:119], v[180:183], v[148:151], v[116:119]
	v_mfma_f32_16x16x32_bf16 v[112:115], v[198:201], v[148:151], v[112:115]
	v_mfma_f32_16x16x32_bf16 v[100:103], v[180:183], v[156:159], v[100:103]
	v_mfma_f32_16x16x32_bf16 v[96:99], v[198:201], v[156:159], v[96:99]
	v_mfma_f32_16x16x32_bf16 v[84:87], v[180:183], v[164:167], v[84:87]
	v_mfma_f32_16x16x32_bf16 v[80:83], v[198:201], v[164:167], v[80:83]
	v_mfma_f32_16x16x32_bf16 v[68:71], v[180:183], v[172:175], v[68:71]
	v_mfma_f32_16x16x32_bf16 v[64:67], v[198:201], v[172:175], v[64:67]
	s_barrier
	ds_read_b128 v[144:147], v217 offset:16384
	ds_read_b128 v[148:151], v217 offset:17408
	ds_read_b128 v[152:155], v217 offset:18432
	ds_read_b128 v[156:159], v217 offset:19456
	s_add_i32 m0, s75, 0x10000
	ds_read_b128 v[160:163], v217 offset:20480
	ds_read_b128 v[164:167], v217 offset:21504
	ds_read_b128 v[168:171], v217 offset:22528
	ds_read_b128 v[172:175], v217 offset:23552
	global_load_lds_dwordx4 v192, s[52:53]
	s_add_i32 m0, s75, 0x12000
	s_nop 0
	global_load_lds_dwordx4 v188, s[52:53]
	s_add_u32 vcc_lo, s52, 0x80000
	s_addc_u32 vcc_hi, s53, 0
	s_add_i32 m0, s75, 0x14000
	s_nop 0
	global_load_lds_dwordx4 v192, vcc
	s_add_i32 m0, s75, 0x16000
	s_nop 0
	global_load_lds_dwordx4 v188, vcc
	s_waitcnt vmcnt(4)
	s_waitcnt lgkmcnt(0)
	s_barrier
	v_mfma_f32_16x16x32_bf16 v[60:63], v[128:131], v[144:147], v[60:63]
	v_mfma_f32_16x16x32_bf16 v[56:59], v[136:139], v[144:147], v[56:59]
	v_mfma_f32_16x16x32_bf16 v[44:47], v[128:131], v[152:155], v[44:47]
	v_mfma_f32_16x16x32_bf16 v[40:43], v[136:139], v[152:155], v[40:43]
	v_mfma_f32_16x16x32_bf16 v[28:31], v[128:131], v[160:163], v[28:31]
	v_mfma_f32_16x16x32_bf16 v[24:27], v[136:139], v[160:163], v[24:27]
	v_mfma_f32_16x16x32_bf16 v[12:15], v[128:131], v[168:171], v[12:15]
	v_mfma_f32_16x16x32_bf16 v[8:11], v[136:139], v[168:171], v[8:11]
	v_mfma_f32_16x16x32_bf16 v[60:63], v[132:135], v[148:151], v[60:63]
	v_mfma_f32_16x16x32_bf16 v[56:59], v[140:143], v[148:151], v[56:59]
	v_mfma_f32_16x16x32_bf16 v[44:47], v[132:135], v[156:159], v[44:47]
	v_mfma_f32_16x16x32_bf16 v[40:43], v[140:143], v[156:159], v[40:43]
	v_mfma_f32_16x16x32_bf16 v[28:31], v[132:135], v[164:167], v[28:31]
	v_mfma_f32_16x16x32_bf16 v[24:27], v[140:143], v[164:167], v[24:27]
	v_mfma_f32_16x16x32_bf16 v[12:15], v[132:135], v[172:175], v[12:15]
	v_mfma_f32_16x16x32_bf16 v[8:11], v[140:143], v[172:175], v[8:11]
	v_mfma_f32_16x16x32_bf16 v[52:55], v[176:179], v[144:147], v[52:55]
	v_mfma_f32_16x16x32_bf16 v[48:51], v[184:187], v[144:147], v[48:51]
	v_mfma_f32_16x16x32_bf16 v[36:39], v[176:179], v[152:155], v[36:39]
	v_mfma_f32_16x16x32_bf16 v[32:35], v[184:187], v[152:155], v[32:35]
	v_mfma_f32_16x16x32_bf16 v[20:23], v[176:179], v[160:163], v[20:23]
	v_mfma_f32_16x16x32_bf16 v[16:19], v[184:187], v[160:163], v[16:19]
	v_mfma_f32_16x16x32_bf16 v[4:7], v[176:179], v[168:171], v[4:7]
	v_mfma_f32_16x16x32_bf16 v[0:3], v[184:187], v[168:171], v[0:3]
	v_mfma_f32_16x16x32_bf16 v[52:55], v[180:183], v[148:151], v[52:55]
	v_mfma_f32_16x16x32_bf16 v[48:51], v[198:201], v[148:151], v[48:51]
	v_mfma_f32_16x16x32_bf16 v[36:39], v[180:183], v[156:159], v[36:39]
	v_mfma_f32_16x16x32_bf16 v[32:35], v[198:201], v[156:159], v[32:35]
	v_mfma_f32_16x16x32_bf16 v[20:23], v[180:183], v[164:167], v[20:23]
	v_mfma_f32_16x16x32_bf16 v[16:19], v[198:201], v[164:167], v[16:19]
	v_mfma_f32_16x16x32_bf16 v[4:7], v[180:183], v[172:175], v[4:7]
	v_mfma_f32_16x16x32_bf16 v[0:3], v[198:201], v[172:175], v[0:3]
	s_barrier
; #define PG8_STAGE(bufoff, gbase, voff) do { _Pragma("unroll") for (int _i = 0; _i < 2; ++_i) \
;         __builtin_amdgcn_global_load_lds((const unsigned*)((const char*)(gbase) + (voff)[_i]), (LAS unsigned*)(lds + (bufoff) + ldsw + _i * 8192), 16, 0, 0); } while (0)
; #define PG8_LDA(dst, b, h) do { _Pragma("unroll") for (int m = 0; m < 4; ++m) _Pragma("unroll") for (int k = 0; k < 2; ++k) dst[m][k] = *(const LAS bf16x8*)(lds + PG8_SA(b, h) + aoff + m * 2048 + k * 1024); } while (0)
; #define PG8_LDB(dst, b, h) do { _Pragma("unroll") for (int n = 0; n < 2; ++n) _Pragma("unroll") for (int k = 0; k < 2; ++k) dst[n][k] = *(const LAS bf16x8*)(lds + PG8_SB(b, h) + boff + n * 2048 + k * 1024); } while (0)
; #define PG8_MMA(ai, bj, At, Bt) do { __builtin_amdgcn_s_setprio(1); _Pragma("unroll") for (int m = 0; m < 4; ++m) _Pragma("unroll") for (int n = 0; n < 2; ++n) _Pragma("unroll") for (int k = 0; k < 2; ++k) \
;         acc[ai][bj][m][n] = __builtin_amdgcn_mfma_f32_16x16x32_bf16(Bt[n][k], At[m][k], acc[ai][bj][m][n], 0, 0, 0); __builtin_amdgcn_s_setprio(0); } while (0)
; #define PG8_WAIT_L(n) asm volatile("s_waitcnt lgkmcnt(" #n ")" ::: "memory")
; #define PG8_BAR __builtin_amdgcn_s_barrier()
; #define PG8_SCHED __builtin_amdgcn_sched_barrier(0)
; template <class Prog>
; __device__ __forceinline__ void gemm_phase(LAS unsigned char* lds, const int K, const Prog& S) {
;     ...
;             PG8_LDB(B0, 1, 0); PG8_SCHED; PG8_LDA(At, 1, 0); PG8_STAGE(PG8_SA(0, 1), a2 + hstep, voffA);
;             PG8_WAIT_L(8); PG8_BAR; PG8_WAIT_L(0); PG8_MMA(0, 0, At, B0); PG8_BAR; PG8_SCHED;
;             PG8_LDB(B1, 1, 1); PG8_STAGE(PG8_SB(1, 0), b3, voffB);
;             PG8_BAR; PG8_WAIT_L(0); PG8_MMA(0, 1, At, B1); PG8_BAR;
;             PG8_LDA(At, 1, 1); PG8_STAGE(PG8_SA(1, 0), a3, voffA);
;             PG8_BAR; PG8_WAIT_L(0); PG8_MMA(1, 0, At, B0); PG8_BAR; PG8_SCHED;
	s_add_u32 vcc_lo, s92, 0x80000
	s_addc_u32 vcc_hi, s93, 0
	ds_read_b128 v[128:131], v202 offset:32768
	ds_read_b128 v[132:135], v202 offset:33792
	ds_read_b128 v[136:139], v202 offset:34816
	ds_read_b128 v[140:143], v202 offset:35840
	s_mov_b32 m0, s75
	ds_read_b128 v[176:179], v202 offset:49152
	ds_read_b128 v[180:183], v202 offset:50176
	ds_read_b128 v[184:187], v202 offset:51200
	ds_read_b128 v[198:201], v202 offset:52224
	global_load_lds_dwordx4 v192, s[92:93]
	s_add_i32 m0, s75, 0x2000
	ds_read_b128 v[144:147], v217 offset:32768
	ds_read_b128 v[148:151], v217 offset:33792
	ds_read_b128 v[152:155], v217 offset:34816
	ds_read_b128 v[156:159], v217 offset:35840
	global_load_lds_dwordx4 v188, s[92:93]
	s_add_i32 m0, s75, 0x4000
	ds_read_b128 v[160:163], v217 offset:36864
	ds_read_b128 v[164:167], v217 offset:37888
	ds_read_b128 v[168:171], v217 offset:38912
	ds_read_b128 v[172:175], v217 offset:39936
	global_load_lds_dwordx4 v192, vcc
	s_add_i32 m0, s75, 0x6000
	s_nop 0
	global_load_lds_dwordx4 v188, vcc
	s_waitcnt lgkmcnt(0)
	s_barrier
	v_mfma_f32_16x16x32_bf16 v[124:127], v[128:131], v[144:147], v[124:127]
	v_mfma_f32_16x16x32_bf16 v[120:123], v[136:139], v[144:147], v[120:123]
	v_mfma_f32_16x16x32_bf16 v[108:111], v[128:131], v[152:155], v[108:111]
	v_mfma_f32_16x16x32_bf16 v[104:107], v[136:139], v[152:155], v[104:107]
	v_mfma_f32_16x16x32_bf16 v[92:95], v[128:131], v[160:163], v[92:95]
	v_mfma_f32_16x16x32_bf16 v[88:91], v[136:139], v[160:163], v[88:91]
	v_mfma_f32_16x16x32_bf16 v[76:79], v[128:131], v[168:171], v[76:79]
	v_mfma_f32_16x16x32_bf16 v[72:75], v[136:139], v[168:171], v[72:75]
	v_mfma_f32_16x16x32_bf16 v[124:127], v[132:135], v[148:151], v[124:127]
	v_mfma_f32_16x16x32_bf16 v[120:123], v[140:143], v[148:151], v[120:123]
	v_mfma_f32_16x16x32_bf16 v[108:111], v[132:135], v[156:159], v[108:111]
	v_mfma_f32_16x16x32_bf16 v[104:107], v[140:143], v[156:159], v[104:107]
	v_mfma_f32_16x16x32_bf16 v[92:95], v[132:135], v[164:167], v[92:95]
	v_mfma_f32_16x16x32_bf16 v[88:91], v[140:143], v[164:167], v[88:91]
	v_mfma_f32_16x16x32_bf16 v[76:79], v[132:135], v[172:175], v[76:79]
	v_mfma_f32_16x16x32_bf16 v[72:75], v[140:143], v[172:175], v[72:75]
	v_mfma_f32_16x16x32_bf16 v[116:119], v[176:179], v[144:147], v[116:119]
	v_mfma_f32_16x16x32_bf16 v[112:115], v[184:187], v[144:147], v[112:115]
	v_mfma_f32_16x16x32_bf16 v[100:103], v[176:179], v[152:155], v[100:103]
	v_mfma_f32_16x16x32_bf16 v[96:99], v[184:187], v[152:155], v[96:99]
	v_mfma_f32_16x16x32_bf16 v[84:87], v[176:179], v[160:163], v[84:87]
	v_mfma_f32_16x16x32_bf16 v[80:83], v[184:187], v[160:163], v[80:83]
	v_mfma_f32_16x16x32_bf16 v[68:71], v[176:179], v[168:171], v[68:71]
	v_mfma_f32_16x16x32_bf16 v[64:67], v[184:187], v[168:171], v[64:67]
	v_mfma_f32_16x16x32_bf16 v[116:119], v[180:183], v[148:151], v[116:119]
	v_mfma_f32_16x16x32_bf16 v[112:115], v[198:201], v[148:151], v[112:115]
	v_mfma_f32_16x16x32_bf16 v[100:103], v[180:183], v[156:159], v[100:103]
	v_mfma_f32_16x16x32_bf16 v[96:99], v[198:201], v[156:159], v[96:99]
	v_mfma_f32_16x16x32_bf16 v[84:87], v[180:183], v[164:167], v[84:87]
	v_mfma_f32_16x16x32_bf16 v[80:83], v[198:201], v[164:167], v[80:83]
	v_mfma_f32_16x16x32_bf16 v[68:71], v[180:183], v[172:175], v[68:71]
	v_mfma_f32_16x16x32_bf16 v[64:67], v[198:201], v[172:175], v[64:67]
	s_nop 0
	s_barrier
	s_add_u32 vcc_lo, s52, 0x80
	s_addc_u32 vcc_hi, s53, 0
	ds_read_b128 v[144:147], v217 offset:49152
	ds_read_b128 v[148:151], v217 offset:50176
	ds_read_b128 v[152:155], v217 offset:51200
	ds_read_b128 v[156:159], v217 offset:52224
	s_add_i32 m0, s75, 0x18000
	ds_read_b128 v[160:163], v217 offset:53248
	ds_read_b128 v[164:167], v217 offset:54272
	ds_read_b128 v[168:171], v217 offset:55296
	ds_read_b128 v[172:175], v217 offset:56320
	global_load_lds_dwordx4 v192, vcc
	s_add_i32 m0, s75, 0x1a000
	s_nop 0
	global_load_lds_dwordx4 v188, vcc
	s_add_u32 vcc_lo, s52, 0x80080
	s_addc_u32 vcc_hi, s53, 0
	s_add_i32 m0, s75, 0x1c000
	s_nop 0
	global_load_lds_dwordx4 v192, vcc
	s_add_i32 m0, s75, 0x1e000
	s_nop 0
	global_load_lds_dwordx4 v188, vcc
	s_waitcnt vmcnt(4)
	s_waitcnt lgkmcnt(0)
	s_barrier
; __device__ __forceinline__ unsigned cvt_pk_bf16(float lo, float hi) { unsigned r; asm volatile("v_cvt_pk_bf16_f32 %0, %1, %2" : "=v"(r) : "v"(lo), "v"(hi)); return r; }
; #define PG8_STAGE(bufoff, gbase, voff) do { _Pragma("unroll") for (int _i = 0; _i < 2; ++_i) \
;         __builtin_amdgcn_global_load_lds((const unsigned*)((const char*)(gbase) + (voff)[_i]), (LAS unsigned*)(lds + (bufoff) + ldsw + _i * 8192), 16, 0, 0); } while (0)
; #define PG8_MMA(ai, bj, At, Bt) do { __builtin_amdgcn_s_setprio(1); _Pragma("unroll") for (int m = 0; m < 4; ++m) _Pragma("unroll") for (int n = 0; n < 2; ++n) _Pragma("unroll") for (int k = 0; k < 2; ++k) \
;         acc[ai][bj][m][n] = __builtin_amdgcn_mfma_f32_16x16x32_bf16(Bt[n][k], At[m][k], acc[ai][bj][m][n], 0, 0, 0); __builtin_amdgcn_s_setprio(0); } while (0)
; template <class Prog>
; __device__ __forceinline__ void gemm_phase(LAS unsigned char* lds, const int K, const Prog& S) {
;     ...
;             PG8_BAR; PG8_WAIT_L(0); PG8_MMA(1, 0, At, B0); PG8_BAR; PG8_SCHED;
;             PG8_STAGE(PG8_SB(1, 1), b3 + hstep, voffB);
;             PG8_WAIT_V(6); PG8_BAR; PG8_MMA(1, 1, At, B1); PG8_BAR;
;     __device__ __forceinline__ void epi(f32x4 (&acc)[2][2][4][2], const pg8::Unit& u, int wr, int wc, int fr, int fq) const {
;     ...
;         for (int ai = 0; ai < 2; ++ai) {
;             f32x4 xo[4][2][2];
; #pragma unroll
;             for (int m = 0; m < 4; ++m)
; #pragma unroll
;                 for (int bj = 0; bj < 2; ++bj)
; #pragma unroll
;                     for (int n = 0; n < 2; ++n) xo[m][bj][n] = *(const f32x4*)(xin + (size_t)(row0 + ai * 128 + m * 16) * DM + col0 + bj * 128 + n * 16);
; #pragma unroll
;             for (int m = 0; m < 4; ++m) {
;                 const int row = row0 + ai * 128 + m * 16;
;                 const size_t off = (size_t)row * DM + col0;
;                 float ss = 0.f;
; #pragma unroll
;                 for (int bj = 0; bj < 2; ++bj)
; #pragma unroll
;                     for (int n = 0; n < 2; ++n) {
;                         const f32x4 o = xo[m][bj][n] + acc[ai][bj][m][n];
;                         *(f32x4*)(xout + off + bj * 128 + n * 16) = o;
;                         ss += o[0] * o[0] + o[1] * o[1] + o[2] * o[2] + o[3] * o[3];
;                         if (rowss_next) { u32x2 w; w.x = cvt_pk_bf16(o[0], o[1]); w.y = cvt_pk_bf16(o[2], o[3]); *(u32x2*)(xb + off + bj * 128 + n * 16) = w; }
	v_mfma_f32_16x16x32_bf16 v[60:63], v[128:131], v[144:147], v[60:63]
	v_mfma_f32_16x16x32_bf16 v[56:59], v[136:139], v[144:147], v[56:59]
	v_mfma_f32_16x16x32_bf16 v[44:47], v[128:131], v[152:155], v[44:47]
	v_mfma_f32_16x16x32_bf16 v[40:43], v[136:139], v[152:155], v[40:43]
	v_mfma_f32_16x16x32_bf16 v[28:31], v[128:131], v[160:163], v[28:31]
	v_mfma_f32_16x16x32_bf16 v[24:27], v[136:139], v[160:163], v[24:27]
	v_mfma_f32_16x16x32_bf16 v[12:15], v[128:131], v[168:171], v[12:15]
	v_mfma_f32_16x16x32_bf16 v[8:11], v[136:139], v[168:171], v[8:11]
	v_mfma_f32_16x16x32_bf16 v[60:63], v[132:135], v[148:151], v[60:63]
	v_mfma_f32_16x16x32_bf16 v[56:59], v[140:143], v[148:151], v[56:59]
	v_mfma_f32_16x16x32_bf16 v[44:47], v[132:135], v[156:159], v[44:47]
	v_mfma_f32_16x16x32_bf16 v[40:43], v[140:143], v[156:159], v[40:43]
	v_mfma_f32_16x16x32_bf16 v[28:31], v[132:135], v[164:167], v[28:31]
	v_mfma_f32_16x16x32_bf16 v[24:27], v[140:143], v[164:167], v[24:27]
	v_mfma_f32_16x16x32_bf16 v[12:15], v[132:135], v[172:175], v[12:15]
	v_mfma_f32_16x16x32_bf16 v[8:11], v[140:143], v[172:175], v[8:11]
	v_mfma_f32_16x16x32_bf16 v[52:55], v[176:179], v[144:147], v[52:55]
	v_mfma_f32_16x16x32_bf16 v[48:51], v[184:187], v[144:147], v[48:51]
	v_mfma_f32_16x16x32_bf16 v[36:39], v[176:179], v[152:155], v[36:39]
	v_mfma_f32_16x16x32_bf16 v[32:35], v[184:187], v[152:155], v[32:35]
	v_mfma_f32_16x16x32_bf16 v[20:23], v[176:179], v[160:163], v[20:23]
	v_mfma_f32_16x16x32_bf16 v[16:19], v[184:187], v[160:163], v[16:19]
	v_mfma_f32_16x16x32_bf16 v[4:7], v[176:179], v[168:171], v[4:7]
	v_mfma_f32_16x16x32_bf16 v[0:3], v[184:187], v[168:171], v[0:3]
	v_mfma_f32_16x16x32_bf16 v[52:55], v[180:183], v[148:151], v[52:55]
	v_mfma_f32_16x16x32_bf16 v[48:51], v[198:201], v[148:151], v[48:51]
	v_mfma_f32_16x16x32_bf16 v[36:39], v[180:183], v[156:159], v[36:39]
	v_mfma_f32_16x16x32_bf16 v[32:35], v[198:201], v[156:159], v[32:35]
	v_mfma_f32_16x16x32_bf16 v[20:23], v[180:183], v[164:167], v[20:23]
	v_mfma_f32_16x16x32_bf16 v[16:19], v[198:201], v[164:167], v[16:19]
	v_mfma_f32_16x16x32_bf16 v[4:7], v[180:183], v[172:175], v[4:7]
	v_mfma_f32_16x16x32_bf16 v[0:3], v[198:201], v[172:175], v[0:3]
	s_add_i32 s54, s54, 2
	s_add_u32 s46, s46, 0x100
	s_addc_u32 s47, s47, 0
	s_add_u32 s41, s41, 0x100
	s_addc_u32 s43, s43, 0
	s_cmp_gt_u32 s54, 29
	s_barrier
	s_cbranch_scc0 .LBB0_571
	v_lshl_add_u32 v202, s80, 8, v214
	v_lshl_or_b32 v198, s73, 8, v216
	v_ashrrev_i32_e32 v199, 31, v198
	v_ashrrev_i32_e32 v203, 31, v202
	v_lshl_add_u64 v[200:201], v[198:199], 2, s[8:9]
	v_lshlrev_b64 v[128:129], 13, v[202:203]
	v_or_b32_e32 v208, 16, v202
	v_lshl_add_u64 v[128:129], v[200:201], 0, v[128:129]
	v_ashrrev_i32_e32 v209, 31, v208
	global_load_dwordx4 v[210:213], v[128:129], off
	global_load_dwordx4 v[184:187], v[128:129], off offset:64
	global_load_dwordx4 v[180:183], v[128:129], off offset:512
	global_load_dwordx4 v[176:179], v[128:129], off offset:576
	v_lshlrev_b64 v[128:129], 13, v[208:209]
	v_or_b32_e32 v206, 32, v202
	v_lshl_add_u64 v[128:129], v[200:201], 0, v[128:129]
	v_ashrrev_i32_e32 v207, 31, v206
	global_load_dwordx4 v[172:175], v[128:129], off
	global_load_dwordx4 v[168:171], v[128:129], off offset:64
	global_load_dwordx4 v[164:167], v[128:129], off offset:512
	global_load_dwordx4 v[160:163], v[128:129], off offset:576
	v_lshlrev_b64 v[128:129], 13, v[206:207]
	v_or_b32_e32 v204, 48, v202
	v_lshl_add_u64 v[128:129], v[200:201], 0, v[128:129]
	v_ashrrev_i32_e32 v205, 31, v204
	global_load_dwordx4 v[156:159], v[128:129], off
	global_load_dwordx4 v[152:155], v[128:129], off offset:64
	global_load_dwordx4 v[148:151], v[128:129], off offset:512
	global_load_dwordx4 v[144:147], v[128:129], off offset:576
	v_lshlrev_b64 v[128:129], 13, v[204:205]
	v_lshl_add_u64 v[128:129], v[200:201], 0, v[128:129]
	global_load_dwordx4 v[140:143], v[128:129], off
	global_load_dwordx4 v[136:139], v[128:129], off offset:64
	global_load_dwordx4 v[132:135], v[128:129], off offset:512
	s_nop 0
	global_load_dwordx4 v[128:131], v[128:129], off offset:576
	v_lshlrev_b64 v[218:219], 11, v[202:203]
	v_lshl_add_u64 v[218:219], v[218:219], 0, v[198:199]
	s_andn2_b64 vcc, exec, s[12:13]
	s_waitcnt vmcnt(0)
	v_pk_add_f32 v[126:127], v[126:127], v[212:213]
	v_cndmask_b32_e64 v212, 0, 1, s[12:13]
	v_pk_add_f32 v[124:125], v[124:125], v[210:211]
	v_lshl_add_u64 v[210:211], v[218:219], 2, s[48:49]
	v_cmp_ne_u32_e64 s[6:7], 1, v212
	v_lshl_add_u64 v[212:213], v[218:219], 1, s[20:21]
	global_store_dwordx4 v[210:211], v[124:127], off
	s_cbranch_vccnz .LBB0_574
	v_cvt_pk_bf16_f32 v218, v124, v125
	v_cvt_pk_bf16_f32 v219, v126, v127
	global_store_dwordx2 v[212:213], v[218:219], off
